# v21 + E28 (attention loops: vmcnt path-merge artifacts removed) + E27 (attention LDS fragment reads software-pipelined in both unit loops)
# speedup vs baseline: 1.0035x; 1.0003x over previous
.LBB0_397:
	v_and_b32_e32 v68, 63, v73
	s_andn2_b64 vcc, exec, s[6:7]
	s_cbranch_vccnz .LBB0_430
	v_lshlrev_b32_e32 v81, 2, v135
	v_and_b32_e32 v81, 12, v81
	v_bfe_u32 v82, v135, 2, 2
	v_lshlrev_b32_e32 v79, 2, v68
	v_cmp_gt_u32_e64 s[4:5], 16, v68
	v_lshlrev_b32_e32 v68, 8, v135
	v_bitop3_b32 v81, v81, v134, v82 bitop3:0x36
	v_lshl_or_b32 v142, v81, 4, v68
	v_add_u32_e32 v68, 0x200, v72
	v_ashrrev_i32_e32 v68, 4, v68
	v_lshlrev_b32_e32 v82, 2, v68
	v_lshlrev_b32_e32 v81, 8, v68
	v_and_b32_e32 v82, 12, v82
	v_bfe_u32 v68, v68, 2, 2
	v_bitop3_b32 v68, v82, v134, v68 bitop3:0x36
	v_lshl_or_b32 v143, v68, 4, v81
	v_add_u32_e32 v68, 0x400, v72
	v_ashrrev_i32_e32 v68, 4, v68
	v_lshlrev_b32_e32 v82, 2, v68
	v_lshlrev_b32_e32 v81, 8, v68
	v_and_b32_e32 v82, 12, v82
	v_bfe_u32 v68, v68, 2, 2
	v_bitop3_b32 v68, v82, v134, v68 bitop3:0x36
	v_lshl_or_b32 v144, v68, 4, v81
	v_add_u32_e32 v68, 0x600, v72
	v_ashrrev_i32_e32 v68, 4, v68
	v_lshlrev_b32_e32 v82, 2, v68
	v_lshlrev_b32_e32 v81, 8, v68
	v_and_b32_e32 v82, 12, v82
	v_bfe_u32 v68, v68, 2, 2
	v_bitop3_b32 v68, v82, v134, v68 bitop3:0x36
	v_lshl_or_b32 v145, v68, 4, v81
	v_add_u32_e32 v68, 0x800, v72
	v_ashrrev_i32_e32 v68, 4, v68
	v_lshlrev_b32_e32 v82, 2, v68
	v_lshlrev_b32_e32 v81, 8, v68
	v_and_b32_e32 v82, 12, v82
	v_bfe_u32 v68, v68, 2, 2
	v_bitop3_b32 v68, v82, v134, v68 bitop3:0x36
	v_lshl_or_b32 v146, v68, 4, v81
	v_add_u32_e32 v68, 0xa00, v72
	v_ashrrev_i32_e32 v68, 4, v68
	v_lshlrev_b32_e32 v82, 2, v68
	v_lshlrev_b32_e32 v81, 8, v68
	v_and_b32_e32 v82, 12, v82
	v_bfe_u32 v68, v68, 2, 2
	v_bitop3_b32 v68, v82, v134, v68 bitop3:0x36
	v_lshl_or_b32 v147, v68, 4, v81
	v_add_u32_e32 v68, 0xc00, v72
	v_ashrrev_i32_e32 v68, 4, v68
	v_lshlrev_b32_e32 v82, 2, v68
	v_lshlrev_b32_e32 v81, 8, v68
	v_and_b32_e32 v82, 12, v82
	v_bfe_u32 v68, v68, 2, 2
	v_bitop3_b32 v68, v82, v134, v68 bitop3:0x36
	v_lshl_or_b32 v148, v68, 4, v81
	v_add_u32_e32 v68, 0xe00, v72
	v_ashrrev_i32_e32 v68, 4, v68
	v_lshlrev_b32_e32 v81, 2, v68
	v_lshlrev_b32_e32 v72, 8, v68
	v_and_b32_e32 v81, 12, v81
	v_bfe_u32 v68, v68, 2, 2
	v_lshlrev_b32_e32 v136, 4, v71
	v_lshlrev_b32_e32 v69, 8, v134
	v_lshlrev_b32_e32 v75, 2, v134
	v_lshlrev_b32_e32 v139, 2, v70
	v_xor_b32_e32 v140, 64, v79
	v_xor_b32_e32 v141, 0x80, v79
	v_lshrrev_b32_e32 v79, 2, v134
	v_bitop3_b32 v68, v81, v134, v68 bitop3:0x36
	v_lshlrev_b32_e32 v71, 12, v71
	s_waitcnt lgkmcnt(0)
	s_add_u32 s24, s8, 0x3e800000
	v_and_b32_e32 v75, 12, v75
	v_bfe_u32 v77, v73, 2, 2
	v_sub_u32_e32 v78, v139, v134
	v_or3_b32 v79, v139, v79, v136
	v_lshl_or_b32 v149, v68, 4, v72
	v_add3_u32 v69, 0, v69, v71
	v_or_b32_e32 v71, 4, v70
	v_or_b32_e32 v72, 8, v70
	v_or_b32_e32 v81, 12, v70
	s_addc_u32 s25, s9, 0
	v_bitop3_b32 v68, v75, v70, v77 bitop3:0x36
	v_bitop3_b32 v71, v75, v71, v77 bitop3:0x36
	v_bitop3_b32 v72, v75, v72, v77 bitop3:0x36
	v_bitop3_b32 v75, v75, v81, v77 bitop3:0x36
	v_cmp_gt_i32_e64 s[6:7], 0, v78
	v_cmp_lt_i32_e64 s[8:9], 0, v78
	v_cmp_gt_i32_e64 s[10:11], -1, v78
	v_cmp_gt_i32_e64 s[12:13], -2, v78
	v_cmp_lt_i32_e32 vcc, -2, v78
	v_cmp_gt_i32_e64 s[14:15], -3, v78
	v_cmp_lt_i32_e64 s[16:17], -3, v78
	v_add_u32_e32 v78, 16, v79
	v_lshlrev_b32_e32 v81, 8, v79
	v_add_u32_e32 v101, 48, v79
	v_add_u32_e32 v105, 0x50, v79
	v_add_u32_e32 v109, 0x70, v79
	v_add_u32_e32 v79, 0x90, v79
	v_min_u32_e32 v78, 0xff, v78
	v_min_u32_e32 v101, 0xff, v101
	v_min_u32_e32 v105, 0xff, v105
	v_min_u32_e32 v109, 0xff, v109
	v_min_u32_e32 v79, 0xff, v79
	v_lshlrev_b32_e32 v83, 2, v78
	v_lshlrev_b32_e32 v103, 2, v101
	v_lshlrev_b32_e32 v107, 2, v105
	v_lshlrev_b32_e32 v111, 2, v109
	v_lshlrev_b32_e32 v114, 2, v79
	v_lshlrev_b32_e32 v1, 3, v73
	v_and_b32_e32 v80, 3, v73
	v_and_b32_e32 v73, 12, v73
	v_lshlrev_b32_e32 v82, 8, v78
	v_and_b32_e32 v83, 12, v83
	v_bfe_u32 v78, v78, 2, 2
	v_lshlrev_b32_e32 v102, 8, v101
	v_and_b32_e32 v103, 12, v103
	v_bfe_u32 v101, v101, 2, 2
	v_lshlrev_b32_e32 v106, 8, v105
	v_and_b32_e32 v107, 12, v107
	v_bfe_u32 v105, v105, 2, 2
	v_lshlrev_b32_e32 v110, 8, v109
	v_and_b32_e32 v111, 12, v111
	v_bfe_u32 v109, v109, 2, 2
	v_lshlrev_b32_e32 v113, 8, v79
	v_and_b32_e32 v114, 12, v114
	v_bfe_u32 v79, v79, 2, 2
	v_bitop3_b32 v77, v70, v80, v73 bitop3:0x36
	v_bitop3_b32 v100, v83, v80, v78 bitop3:0x36
	v_bitop3_b32 v104, v103, v80, v101 bitop3:0x36
	v_bitop3_b32 v108, v107, v80, v105 bitop3:0x36
	v_bitop3_b32 v112, v111, v80, v109 bitop3:0x36
	v_bitop3_b32 v115, v114, v80, v79 bitop3:0x36
	v_or_b32_e32 v116, 4, v80
	v_or_b32_e32 v122, 8, v80
	v_or_b32_e32 v80, 12, v80
	v_lshlrev_b32_e32 v76, 3, v70
	s_add_i32 s53, 0, 0x10000
	v_bitop3_b32 v117, v70, v116, v73 bitop3:0x36
	v_bitop3_b32 v118, v83, v116, v78 bitop3:0x36
	v_bitop3_b32 v119, v103, v116, v101 bitop3:0x36
	v_bitop3_b32 v120, v107, v116, v105 bitop3:0x36
	v_bitop3_b32 v121, v111, v116, v109 bitop3:0x36
	v_bitop3_b32 v116, v114, v116, v79 bitop3:0x36
	v_bitop3_b32 v123, v70, v122, v73 bitop3:0x36
	v_bitop3_b32 v124, v83, v122, v78 bitop3:0x36
	v_bitop3_b32 v125, v103, v122, v101 bitop3:0x36
	v_bitop3_b32 v126, v107, v122, v105 bitop3:0x36
	v_bitop3_b32 v127, v111, v122, v109 bitop3:0x36
	v_bitop3_b32 v122, v114, v122, v79 bitop3:0x36
	v_bitop3_b32 v70, v70, v80, v73 bitop3:0x36
	v_bitop3_b32 v73, v83, v80, v78 bitop3:0x36
	v_bitop3_b32 v78, v103, v80, v101 bitop3:0x36
	v_bitop3_b32 v83, v107, v80, v105 bitop3:0x36
	v_bitop3_b32 v101, v111, v80, v109 bitop3:0x36
	v_bitop3_b32 v79, v114, v80, v79 bitop3:0x36
	v_and_b32_e32 v74, 0x78, v1
	v_lshlrev_b32_e32 v68, 4, v68
	v_lshlrev_b32_e32 v71, 4, v71
	v_lshlrev_b32_e32 v72, 4, v72
	v_lshlrev_b32_e32 v75, 4, v75
	v_lshl_add_u32 v77, v77, 4, s53
	v_lshl_add_u32 v100, v100, 4, s53
	v_lshl_add_u32 v104, v104, 4, s53
	v_lshl_add_u32 v108, v108, 4, s53
	v_lshl_add_u32 v112, v112, 4, s53
	v_lshl_add_u32 v115, v115, 4, s53
	v_lshl_add_u32 v117, v117, 4, s53
	v_lshl_add_u32 v118, v118, 4, s53
	v_lshl_add_u32 v119, v119, 4, s53
	v_lshl_add_u32 v120, v120, 4, s53
	v_lshl_add_u32 v121, v121, 4, s53
	v_lshl_add_u32 v116, v116, 4, s53
	v_lshl_add_u32 v123, v123, 4, s53
	v_lshl_add_u32 v124, v124, 4, s53
	v_lshl_add_u32 v125, v125, 4, s53
	v_lshl_add_u32 v126, v126, 4, s53
	v_lshl_add_u32 v127, v127, 4, s53
	v_lshl_add_u32 v122, v122, 4, s53
	v_lshl_add_u32 v70, v70, 4, s53
	v_lshl_add_u32 v73, v73, 4, s53
	v_lshl_add_u32 v78, v78, 4, s53
	v_lshl_add_u32 v83, v83, 4, s53
	v_lshl_add_u32 v101, v101, 4, s53
	v_lshl_add_u32 v79, v79, 4, s53
	v_subrev_u32_e32 v137, 64, v135
	v_mov_b32_e32 v1, v0
	v_mov_b32_e32 v2, v0
	v_mov_b32_e32 v3, v0
	v_or_b32_e32 v138, v136, v134
	v_or_b32_e32 v150, 0xffffffc0, v139
	v_or_b32_e32 v151, 0xffffffd0, v139
	v_or_b32_e32 v152, 0xffffffe0, v139
	v_or_b32_e32 v153, -16, v139
	v_or_b32_e32 v154, 16, v139
	v_or_b32_e32 v155, 32, v139
	v_or_b32_e32 v156, 48, v139
	v_or_b32_e32 v157, 64, v139
	v_lshlrev_b32_e32 v200, 1, v74
	v_add_u32_e32 v158, v69, v68
	v_add_u32_e32 v159, v69, v71
	v_add_u32_e32 v160, v69, v72
	v_add_u32_e32 v161, v69, v75
	v_lshlrev_b32_e32 v132, 1, v76
	v_add_u32_e32 v162, v77, v81
	v_add_u32_e32 v163, v100, v82
	v_add_u32_e32 v164, v104, v102
	v_add_u32_e32 v165, v108, v106
	v_add_u32_e32 v166, v112, v110
	v_add_u32_e32 v167, v115, v113
	v_add_u32_e32 v168, v117, v81
	v_add_u32_e32 v169, v118, v82
	v_add_u32_e32 v170, v119, v102
	v_add_u32_e32 v171, v120, v106
	v_add_u32_e32 v172, v121, v110
	v_add_u32_e32 v173, v116, v113
	v_add_u32_e32 v174, v123, v81
	v_add_u32_e32 v175, v124, v82
	v_add_u32_e32 v176, v125, v102
	v_add_u32_e32 v177, v126, v106
	v_add_u32_e32 v178, v127, v110
	v_add_u32_e32 v179, v122, v113
	v_add_u32_e32 v180, v70, v81
	v_add_u32_e32 v181, v73, v82
	v_add_u32_e32 v182, v78, v102
	v_add_u32_e32 v183, v83, v106
	v_add_u32_e32 v184, v101, v110
	v_add_u32_e32 v185, v79, v113
	s_and_b64 s[18:19], s[16:17], vcc
	s_waitcnt vmcnt(0)
	s_branch .LBB0_400

.LBB0_404:
	v_add_u32_e32 v68, 0, v142
	s_nop 0
	ds_write_b128 v68, v[4:7]
	v_add_u32_e32 v68, s53, v142
	s_nop 0
	ds_write_b128 v68, v[8:11]
	v_add_u32_e32 v68, 0, v143
	ds_write_b128 v68, v[12:15]
	v_add_u32_e32 v68, s53, v143
	ds_write_b128 v68, v[16:19]
	v_add_u32_e32 v68, 0, v144
	ds_write_b128 v68, v[20:23]
	v_add_u32_e32 v68, s53, v144
	ds_write_b128 v68, v[24:27]
	v_add_u32_e32 v68, 0, v145
	ds_write_b128 v68, v[28:31]
	v_add_u32_e32 v68, s53, v145
	ds_write_b128 v68, v[32:35]
	v_add_u32_e32 v68, 0, v146
	ds_write_b128 v68, v[40:43]
	v_add_u32_e32 v68, s53, v146
	ds_write_b128 v68, v[44:47]
	v_add_u32_e32 v68, 0, v147
	ds_write_b128 v68, v[48:51]
	v_add_u32_e32 v68, s53, v147
	ds_write_b128 v68, v[52:55]
	v_add_u32_e32 v68, 0, v148
	ds_write_b128 v68, v[56:59]
	v_add_u32_e32 v68, s53, v148
	ds_write_b128 v68, v[60:63]
	v_add_u32_e32 v68, 0, v149
	ds_write_b128 v68, v[64:67]
	v_add_u32_e32 v68, s53, v149
	ds_write_b128 v68, v[36:39]
	s_add_i32 s62, s31, 32
	s_waitcnt lgkmcnt(0)
	s_barrier
	s_cmpk_gt_i32 s31, 0x1df
	s_cselect_b64 s[26:27], -1, 0
	s_nop 0
	v_mov_b64_e32 v[68:69], v[96:97]
	s_nop 0
	v_mov_b64_e32 v[72:73], v[92:93]
	s_nop 0
	v_mov_b64_e32 v[76:77], v[88:89]
	s_nop 0
	v_mov_b64_e32 v[80:81], v[84:85]
	s_and_b64 vcc, exec, s[26:27]
	v_mov_b64_e32 v[70:71], v[98:99]
	v_mov_b64_e32 v[74:75], v[94:95]
	v_mov_b64_e32 v[78:79], v[90:91]
	v_mov_b64_e32 v[82:83], v[86:87]
	s_cbranch_vccnz .LBB0_426
	s_lshr_b32 s36, s62, 3
	s_ashr_i32 s37, s62, 8
	s_and_b32 s20, s36, 24
	s_or_b32 s39, s20, s49
	s_lshl_b32 s29, s37, 1
	s_mov_b64 s[20:21], -1
	s_and_b64 vcc, exec, s[22:23]
	s_cbranch_vccz .LBB0_407
	s_sub_i32 s20, 5, s29
	s_lshr_b32 s38, s39, s20
	s_lshl_b32 s21, s41, s20
	s_lshl_b32 s20, -1, s20
	s_andn2_b32 s20, s39, s20
	s_add_i32 s68, s20, s21
	s_mov_b64 s[20:21], 0

.LBB0_517:
	v_and_b32_e32 v68, 63, v73
	s_andn2_b64 vcc, exec, s[6:7]
	s_cbranch_vccnz .LBB0_548
	v_lshlrev_b32_e32 v84, 2, v169
	v_and_b32_e32 v84, 12, v84
	v_bfe_u32 v85, v169, 2, 2
	v_lshlrev_b32_e32 v83, 8, v169
	v_bitop3_b32 v84, v84, v168, v85 bitop3:0x36
	v_lshl_or_b32 v176, v84, 4, v83
	v_add_u32_e32 v83, 0x200, v72
	v_ashrrev_i32_e32 v83, 4, v83
	v_lshlrev_b32_e32 v85, 2, v83
	v_lshlrev_b32_e32 v84, 8, v83
	v_and_b32_e32 v85, 12, v85
	v_bfe_u32 v83, v83, 2, 2
	v_bitop3_b32 v83, v85, v168, v83 bitop3:0x36
	v_lshl_or_b32 v177, v83, 4, v84
	v_add_u32_e32 v83, 0x400, v72
	v_ashrrev_i32_e32 v83, 4, v83
	v_lshlrev_b32_e32 v85, 2, v83
	v_lshlrev_b32_e32 v84, 8, v83
	v_and_b32_e32 v85, 12, v85
	v_bfe_u32 v83, v83, 2, 2
	v_bitop3_b32 v83, v85, v168, v83 bitop3:0x36
	v_lshl_or_b32 v178, v83, 4, v84
	v_add_u32_e32 v83, 0x600, v72
	v_ashrrev_i32_e32 v83, 4, v83
	v_lshlrev_b32_e32 v85, 2, v83
	v_lshlrev_b32_e32 v84, 8, v83
	v_and_b32_e32 v85, 12, v85
	v_bfe_u32 v83, v83, 2, 2
	v_bitop3_b32 v83, v85, v168, v83 bitop3:0x36
	v_lshl_or_b32 v179, v83, 4, v84
	v_add_u32_e32 v83, 0x800, v72
	v_ashrrev_i32_e32 v83, 4, v83
	v_lshlrev_b32_e32 v85, 2, v83
	v_lshlrev_b32_e32 v84, 8, v83
	v_and_b32_e32 v85, 12, v85
	v_bfe_u32 v83, v83, 2, 2
	v_bitop3_b32 v83, v85, v168, v83 bitop3:0x36
	v_lshl_or_b32 v180, v83, 4, v84
	v_add_u32_e32 v83, 0xa00, v72
	v_ashrrev_i32_e32 v83, 4, v83
	v_lshlrev_b32_e32 v85, 2, v83
	v_lshlrev_b32_e32 v84, 8, v83
	v_and_b32_e32 v85, 12, v85
	v_bfe_u32 v83, v83, 2, 2
	v_bitop3_b32 v83, v85, v168, v83 bitop3:0x36
	v_lshl_or_b32 v181, v83, 4, v84
	v_add_u32_e32 v83, 0xc00, v72
	v_ashrrev_i32_e32 v83, 4, v83
	v_lshlrev_b32_e32 v85, 2, v83
	s_waitcnt lgkmcnt(0)
	s_add_u32 s24, s8, 0x3e800000
	v_lshlrev_b32_e32 v68, 2, v68
	v_lshlrev_b32_e32 v84, 8, v83
	v_and_b32_e32 v85, 12, v85
	v_bfe_u32 v83, v83, 2, 2
	v_add_u32_e32 v72, 0xe00, v72
	s_addc_u32 s25, s9, 0
	v_lshlrev_b32_e32 v170, 4, v71
	v_lshlrev_b32_e32 v173, 2, v70
	v_xor_b32_e32 v174, 64, v68
	v_xor_b32_e32 v175, 0x80, v68
	v_lshrrev_b32_e32 v68, 2, v168
	v_bitop3_b32 v83, v85, v168, v83 bitop3:0x36
	v_ashrrev_i32_e32 v72, 4, v72
	s_add_u32 s40, s10, 0x3a800000
	v_sub_u32_e32 v78, v173, v168
	v_or3_b32 v68, v173, v68, v170
	v_lshl_or_b32 v182, v83, 4, v84
	v_lshlrev_b32_e32 v84, 2, v72
	s_addc_u32 s41, s11, 0
	v_lshlrev_b32_e32 v82, 8, v68
	v_lshlrev_b32_e32 v83, 8, v72
	v_and_b32_e32 v84, 12, v84
	v_bfe_u32 v72, v72, 2, 2
	v_cmp_gt_i32_e64 s[4:5], 0, v78
	v_cmp_lt_i32_e64 s[6:7], 0, v78
	v_cmp_gt_i32_e64 s[8:9], -1, v78
	v_cmp_gt_i32_e64 s[10:11], -2, v78
	v_cmp_lt_i32_e32 vcc, -2, v78
	v_cmp_gt_i32_e64 s[12:13], -3, v78
	v_cmp_lt_i32_e64 s[14:15], -3, v78
	v_add_u32_e32 v78, 16, v68
	v_add_u32_e32 v87, 48, v68
	v_add_u32_e32 v91, 0x50, v68
	v_add_u32_e32 v95, 0x70, v68
	v_add_u32_e32 v68, 0x90, v68
	v_lshlrev_b32_e32 v69, 8, v168
	v_lshlrev_b32_e32 v75, 2, v168
	v_bitop3_b32 v72, v84, v168, v72 bitop3:0x36
	v_lshlrev_b32_e32 v71, 12, v71
	v_min_u32_e32 v78, 0xff, v78
	v_min_u32_e32 v87, 0xff, v87
	v_min_u32_e32 v91, 0xff, v91
	v_min_u32_e32 v95, 0xff, v95
	v_min_u32_e32 v68, 0xff, v68
	v_and_b32_e32 v75, 12, v75
	v_bfe_u32 v77, v73, 2, 2
	v_lshl_or_b32 v183, v72, 4, v83
	v_add3_u32 v69, 0, v69, v71
	v_or_b32_e32 v71, 4, v70
	v_or_b32_e32 v83, 8, v70
	v_or_b32_e32 v84, 12, v70
	v_lshlrev_b32_e32 v85, 2, v78
	v_lshlrev_b32_e32 v89, 2, v87
	v_lshlrev_b32_e32 v93, 2, v91
	v_lshlrev_b32_e32 v97, 2, v95
	v_lshlrev_b32_e32 v100, 2, v68
	v_lshlrev_b32_e32 v1, 3, v73
	v_and_b32_e32 v79, 3, v73
	v_and_b32_e32 v73, 12, v73
	v_bitop3_b32 v72, v75, v70, v77 bitop3:0x36
	v_bitop3_b32 v71, v75, v71, v77 bitop3:0x36
	v_bitop3_b32 v83, v75, v83, v77 bitop3:0x36
	v_bitop3_b32 v75, v75, v84, v77 bitop3:0x36
	v_lshlrev_b32_e32 v84, 8, v78
	v_and_b32_e32 v85, 12, v85
	v_bfe_u32 v78, v78, 2, 2
	v_lshlrev_b32_e32 v88, 8, v87
	v_and_b32_e32 v89, 12, v89
	v_bfe_u32 v87, v87, 2, 2
	v_lshlrev_b32_e32 v92, 8, v91
	v_and_b32_e32 v93, 12, v93
	v_bfe_u32 v91, v91, 2, 2
	v_lshlrev_b32_e32 v96, 8, v95
	v_and_b32_e32 v97, 12, v97
	v_bfe_u32 v95, v95, 2, 2
	v_lshlrev_b32_e32 v99, 8, v68
	v_and_b32_e32 v100, 12, v100
	v_bfe_u32 v68, v68, 2, 2
	v_or_b32_e32 v80, 12, v79
	v_bitop3_b32 v77, v70, v79, v73 bitop3:0x36
	v_bitop3_b32 v86, v85, v79, v78 bitop3:0x36
	v_bitop3_b32 v90, v89, v79, v87 bitop3:0x36
	v_bitop3_b32 v94, v93, v79, v91 bitop3:0x36
	v_bitop3_b32 v98, v97, v79, v95 bitop3:0x36
	v_bitop3_b32 v101, v100, v79, v68 bitop3:0x36
	v_or_b32_e32 v102, 4, v79
	v_or_b32_e32 v79, 8, v79
	v_lshlrev_b32_e32 v74, 3, v70
	v_bitop3_b32 v81, v70, v80, v73 bitop3:0x36
	s_add_i32 s42, 0, 0x10000
	v_bitop3_b32 v103, v70, v102, v73 bitop3:0x36
	v_bitop3_b32 v104, v85, v102, v78 bitop3:0x36
	v_bitop3_b32 v105, v89, v102, v87 bitop3:0x36
	v_bitop3_b32 v106, v93, v102, v91 bitop3:0x36
	v_bitop3_b32 v107, v97, v102, v95 bitop3:0x36
	v_bitop3_b32 v102, v100, v102, v68 bitop3:0x36
	v_bitop3_b32 v70, v70, v79, v73 bitop3:0x36
	v_bitop3_b32 v73, v85, v79, v78 bitop3:0x36
	v_bitop3_b32 v108, v89, v79, v87 bitop3:0x36
	v_bitop3_b32 v109, v93, v79, v91 bitop3:0x36
	v_bitop3_b32 v110, v97, v79, v95 bitop3:0x36
	v_bitop3_b32 v79, v100, v79, v68 bitop3:0x36
	v_bitop3_b32 v78, v85, v80, v78 bitop3:0x36
	v_bitop3_b32 v85, v89, v80, v87 bitop3:0x36
	v_bitop3_b32 v87, v93, v80, v91 bitop3:0x36
	v_bitop3_b32 v89, v97, v80, v95 bitop3:0x36
	v_bitop3_b32 v68, v100, v80, v68 bitop3:0x36
	v_and_b32_e32 v76, 0x78, v1
	v_lshl_add_u32 v81, v81, 4, s42
	v_lshlrev_b32_e32 v72, 4, v72
	v_lshlrev_b32_e32 v71, 4, v71
	v_lshlrev_b32_e32 v83, 4, v83
	v_lshlrev_b32_e32 v75, 4, v75
	v_lshl_add_u32 v77, v77, 4, s42
	v_lshl_add_u32 v86, v86, 4, s42
	v_lshl_add_u32 v90, v90, 4, s42
	v_lshl_add_u32 v94, v94, 4, s42
	v_lshl_add_u32 v98, v98, 4, s42
	v_lshl_add_u32 v101, v101, 4, s42
	v_lshl_add_u32 v103, v103, 4, s42
	v_lshl_add_u32 v104, v104, 4, s42
	v_lshl_add_u32 v105, v105, 4, s42
	v_lshl_add_u32 v106, v106, 4, s42
	v_lshl_add_u32 v107, v107, 4, s42
	v_lshl_add_u32 v102, v102, 4, s42
	v_lshl_add_u32 v70, v70, 4, s42
	v_lshl_add_u32 v73, v73, 4, s42
	v_lshl_add_u32 v108, v108, 4, s42
	v_lshl_add_u32 v109, v109, 4, s42
	v_lshl_add_u32 v110, v110, 4, s42
	v_lshl_add_u32 v79, v79, 4, s42
	v_lshl_add_u32 v78, v78, 4, s42
	v_lshl_add_u32 v85, v85, 4, s42
	v_lshl_add_u32 v87, v87, 4, s42
	v_lshl_add_u32 v89, v89, 4, s42
	v_lshl_add_u32 v68, v68, 4, s42
	v_subrev_u32_e32 v171, 64, v169
	v_mov_b32_e32 v1, v0
	v_mov_b32_e32 v2, v0
	v_mov_b32_e32 v3, v0
	v_or_b32_e32 v172, v170, v168
	v_or_b32_e32 v184, 0xffffffc0, v173
	v_or_b32_e32 v185, 0xffffffd0, v173
	v_or_b32_e32 v186, 0xffffffe0, v173
	v_or_b32_e32 v187, -16, v173
	v_or_b32_e32 v188, 16, v173
	v_or_b32_e32 v189, 32, v173
	v_or_b32_e32 v190, 48, v173
	v_or_b32_e32 v191, 64, v173
	s_add_i32 s43, s18, 0x220
	v_lshlrev_b32_e32 v164, 1, v76
	v_add_u32_e32 v192, v69, v72
	v_add_u32_e32 v193, v69, v71
	v_add_u32_e32 v194, v69, v83
	v_add_u32_e32 v195, v69, v75
	v_lshlrev_b32_e32 v200, 1, v74
	v_add_u32_e32 v196, v77, v82
	v_add_u32_e32 v197, v86, v84
	v_add_u32_e32 v198, v90, v88
	v_add_u32_e32 v199, v94, v92
	v_add_u32_e32 v202, v98, v96
	v_add_u32_e32 v203, v101, v99
	v_add_u32_e32 v204, v103, v82
	v_add_u32_e32 v205, v104, v84
	v_add_u32_e32 v206, v105, v88
	v_add_u32_e32 v207, v106, v92
	v_add_u32_e32 v212, v107, v96
	v_add_u32_e32 v213, v102, v99
	v_add_u32_e32 v214, v70, v82
	v_add_u32_e32 v215, v73, v84
	v_add_u32_e32 v216, v108, v88
	v_add_u32_e32 v217, v109, v92
	v_add_u32_e32 v218, v110, v96
	v_add_u32_e32 v219, v79, v99
	v_add_u32_e32 v220, v81, v82
	v_add_u32_e32 v221, v78, v84
	v_add_u32_e32 v222, v85, v88
	v_add_u32_e32 v223, v87, v92
	v_add_u32_e32 v224, v89, v96
	v_add_u32_e32 v225, v68, v99
	s_and_b64 s[16:17], s[14:15], vcc
	s_waitcnt vmcnt(0)
	s_branch .LBB0_520
.LBB0_519:
	ds_read_b64_tr_b16 v[228:229], v197
	ds_read_b64_tr_b16 v[226:227], v196
	ds_read_b64_tr_b16 v[230:231], v196 offset:8192
	ds_read_b64_tr_b16 v[232:233], v198
	ds_read_b64_tr_b16 v[234:235], v196 offset:16384
	ds_read_b64_tr_b16 v[236:237], v199
	s_mov_b32 s18, 0xff61b1e6
	v_max3_f32 v124, v122, s18, v123
	v_max3_f32 v124, v124, v120, v121
	v_max3_f32 v124, v124, v156, v157
	v_max3_f32 v124, v124, v158, v159
	v_max3_f32 v124, v124, v152, v153
	v_max3_f32 v124, v124, v154, v155
	v_max3_f32 v124, v124, v148, v149
	v_max3_f32 v124, v124, v150, v151
	v_max3_f32 v124, v124, v144, v145
	v_max3_f32 v124, v124, v146, v147
	v_max3_f32 v124, v124, v140, v141
	v_max3_f32 v124, v124, v142, v143
	v_max3_f32 v124, v124, v136, v137
	v_max3_f32 v124, v124, v138, v139
	v_max3_f32 v124, v124, v132, v133
	v_max3_f32 v124, v124, v134, v135
	v_max3_f32 v124, v124, v118, v119
	v_max3_f32 v124, v124, v116, v117
	ds_bpermute_b32 v125, v174, v124
	s_nop 0
	s_waitcnt lgkmcnt(0)
	v_max_f32_e32 v125, v125, v125
	v_max_f32_e32 v124, v124, v125
	ds_bpermute_b32 v125, v175, v124
	s_nop 0
	s_waitcnt lgkmcnt(0)
	v_max_f32_e32 v125, v125, v125
	v_max_f32_e32 v160, v124, v125
	v_sub_f32_e32 v122, v122, v160
	v_exp_f32_e32 v122, v122
	v_sub_f32_e32 v123, v123, v160
	v_exp_f32_e32 v123, v123
	v_sub_f32_e32 v120, v120, v160
	v_exp_f32_e32 v120, v120
	v_sub_f32_e32 v121, v121, v160
	v_exp_f32_e32 v121, v121
	v_sub_f32_e32 v125, v156, v160
	v_add_f32_e32 v124, 0, v122
	v_exp_f32_e32 v126, v125
	v_sub_f32_e32 v125, v157, v160
	v_add_f32_e32 v124, v123, v124
	v_exp_f32_e32 v127, v125
	v_sub_f32_e32 v125, v158, v160
	v_add_f32_e32 v124, v120, v124
	v_exp_f32_e32 v128, v125
	v_sub_f32_e32 v125, v159, v160
	v_add_f32_e32 v124, v121, v124
	v_exp_f32_e32 v129, v125
	v_sub_f32_e32 v125, v152, v160
	v_add_f32_e32 v124, v126, v124
	v_exp_f32_e32 v130, v125
	v_sub_f32_e32 v125, v153, v160
	v_add_f32_e32 v124, v127, v124
	v_exp_f32_e32 v131, v125
	v_sub_f32_e32 v125, v154, v160
	v_add_f32_e32 v124, v128, v124
	v_exp_f32_e32 v152, v125
	v_sub_f32_e32 v125, v155, v160
	v_add_f32_e32 v124, v129, v124
	v_exp_f32_e32 v153, v125
	v_sub_f32_e32 v125, v148, v160
	v_add_f32_e32 v124, v130, v124
	v_exp_f32_e32 v148, v125
	v_sub_f32_e32 v125, v149, v160
	v_add_f32_e32 v124, v131, v124
	v_exp_f32_e32 v149, v125
	v_sub_f32_e32 v125, v150, v160
	v_add_f32_e32 v124, v152, v124
	v_exp_f32_e32 v150, v125
	v_sub_f32_e32 v125, v151, v160
	v_add_f32_e32 v124, v153, v124
	v_exp_f32_e32 v151, v125
	v_sub_f32_e32 v125, v144, v160
	v_add_f32_e32 v124, v148, v124
	v_exp_f32_e32 v144, v125
	v_sub_f32_e32 v125, v145, v160
	v_add_f32_e32 v124, v149, v124
	v_exp_f32_e32 v145, v125
	v_sub_f32_e32 v125, v146, v160
	v_add_f32_e32 v124, v150, v124
	v_exp_f32_e32 v146, v125
	v_sub_f32_e32 v125, v147, v160
	v_add_f32_e32 v124, v151, v124
	v_exp_f32_e32 v147, v125
	v_sub_f32_e32 v125, v140, v160
	v_add_f32_e32 v124, v144, v124
	v_exp_f32_e32 v140, v125
	v_sub_f32_e32 v125, v141, v160
	v_add_f32_e32 v124, v145, v124
	v_exp_f32_e32 v141, v125
	v_sub_f32_e32 v125, v142, v160
	v_add_f32_e32 v124, v146, v124
	v_exp_f32_e32 v142, v125
	v_sub_f32_e32 v125, v143, v160
	v_add_f32_e32 v124, v147, v124
	v_exp_f32_e32 v143, v125
	v_sub_f32_e32 v125, v136, v160
	v_add_f32_e32 v124, v140, v124
	v_exp_f32_e32 v136, v125
	v_sub_f32_e32 v125, v137, v160
	v_add_f32_e32 v124, v141, v124
	v_exp_f32_e32 v137, v125
	v_sub_f32_e32 v125, v138, v160
	v_add_f32_e32 v124, v142, v124
	v_exp_f32_e32 v138, v125
	v_sub_f32_e32 v125, v139, v160
	v_add_f32_e32 v124, v143, v124
	v_exp_f32_e32 v139, v125
	v_sub_f32_e32 v125, v132, v160
	v_add_f32_e32 v124, v136, v124
	v_exp_f32_e32 v154, v125
	v_sub_f32_e32 v125, v133, v160
	v_add_f32_e32 v124, v137, v124
	v_exp_f32_e32 v155, v125
	v_sub_f32_e32 v125, v134, v160
	v_add_f32_e32 v124, v138, v124
	v_exp_f32_e32 v156, v125
	v_sub_f32_e32 v125, v135, v160
	v_add_f32_e32 v124, v139, v124
	v_exp_f32_e32 v157, v125
	v_sub_f32_e32 v118, v118, v160
	v_add_f32_e32 v124, v154, v124
	v_exp_f32_e32 v118, v118
	v_sub_f32_e32 v119, v119, v160
	v_add_f32_e32 v124, v155, v124
	v_exp_f32_e32 v119, v119
	v_sub_f32_e32 v116, v116, v160
	v_add_f32_e32 v124, v156, v124
	v_exp_f32_e32 v158, v116
	v_sub_f32_e32 v117, v117, v160
	v_add_f32_e32 v124, v157, v124
	v_exp_f32_e32 v117, v117
	v_add_f32_e32 v124, v118, v124
	v_add_f32_e32 v124, v119, v124
	v_add_f32_e32 v116, v158, v124
	v_add_f32_e32 v116, v117, v116
	ds_bpermute_b32 v124, v174, v116
	s_nop 0
	s_waitcnt lgkmcnt(0)
	v_add_f32_e32 v159, v116, v124
	ds_bpermute_b32 v161, v175, v159
	v_cvt_pk_bf16_f32 v124, v122, v123
	v_cvt_pk_bf16_f32 v125, v120, v121
	v_cvt_pk_bf16_f32 v126, v126, v127
	v_cvt_pk_bf16_f32 v127, v128, v129
	v_cvt_pk_bf16_f32 v128, v130, v131
	v_cvt_pk_bf16_f32 v129, v152, v153
	v_cvt_pk_bf16_f32 v130, v148, v149
	v_cvt_pk_bf16_f32 v131, v150, v151
	v_cvt_pk_bf16_f32 v132, v144, v145
	v_cvt_pk_bf16_f32 v133, v146, v147
	v_cvt_pk_bf16_f32 v134, v140, v141
	v_cvt_pk_bf16_f32 v135, v142, v143
	v_cvt_pk_bf16_f32 v120, v136, v137
	s_nop 0
	s_waitcnt lgkmcnt(0)
	v_add_f32_e32 v136, v159, v161
	v_div_scale_f32 v137, s[18:19], v136, v136, 1.0
	v_cvt_pk_bf16_f32 v121, v138, v139
	v_rcp_f32_e32 v138, v137
	s_mov_b32 s18, 0x3f317218
	v_cvt_pk_bf16_f32 v122, v154, v155
	v_cvt_pk_bf16_f32 v123, v156, v157
	v_fma_f32 v139, -v137, v138, 1.0
	v_fmac_f32_e32 v138, v139, v138
	v_div_scale_f32 v139, vcc, 1.0, v136, 1.0
	v_mul_f32_e32 v140, v139, v138
	v_fma_f32 v141, -v137, v140, v139
	v_fmac_f32_e32 v140, v141, v138
	v_fma_f32 v137, -v137, v140, v139
	v_div_fmas_f32 v137, v137, v138, v140
	v_div_fixup_f32 v137, v137, v136, 1.0
	v_log_f32_e32 v136, v136
	v_cvt_pk_bf16_f32 v116, v118, v119
	v_cvt_pk_bf16_f32 v117, v158, v117
	v_mov_b32_e32 v118, v201
	v_add_f32_e32 v136, v160, v136
	v_mul_f32_e32 v138, 0x3f317218, v136
	s_waitcnt vmcnt(28)
	s_cmpk_lt_i32 s48, 0x2e0
	s_cbranch_scc1 .LE28_a
	s_waitcnt vmcnt(8)
.LE28_a:
	v_max3_f32 v138, v209, v208, v138
	v_sub_f32_e32 v139, v209, v138
	v_mul_f32_e32 v139, 0x3fb8aa3b, v139
	v_exp_f32_e32 v140, v139
	v_sub_f32_e32 v139, v208, v138
	v_mul_f32_e32 v139, 0x3fb8aa3b, v139
	v_fma_f32 v136, v136, s18, -v138
	v_exp_f32_e32 v141, v139
	v_mul_f32_e32 v136, 0x3fb8aa3b, v136
	v_exp_f32_e32 v136, v136
	v_mov_b32_e32 v119, v201
	v_add_f32_e32 v138, v140, v141
	v_add_f32_e32 v138, v136, v138
	v_div_scale_f32 v139, s[18:19], v138, v138, 1.0
	v_rcp_f32_e32 v142, v139
	s_lshl_b32 s18, s26, 1
	s_add_u32 s18, s40, s18
	s_addc_u32 s19, s41, 0
	v_fma_f32 v143, -v139, v142, 1.0
	v_fmac_f32_e32 v142, v143, v142
	v_div_scale_f32 v143, vcc, 1.0, v138, 1.0
	v_mul_f32_e32 v144, v143, v142
	v_fma_f32 v145, -v139, v144, v143
	v_fmac_f32_e32 v144, v145, v142
	v_fma_f32 v139, -v139, v144, v143
	v_div_fmas_f32 v139, v139, v142, v144
	s_nop 0
	s_nop 0
	s_nop 0
	s_nop 0
	s_nop 0
	ds_read_b64_tr_b16 v[246:247], v196 offset:24576
	ds_read_b64_tr_b16 v[248:249], v202
	v_mfma_f32_16x16x32_bf16 v[144:147], v[226:229], v[124:127], 0
	s_nop 0
	s_nop 0
	s_nop 0
	v_div_fixup_f32 v142, v139, v138, 1.0
	v_mul_f32_e32 v136, v136, v142
	s_nop 0
	ds_read_b64_tr_b16 v[250:251], v196 offset:32768
	ds_read_b64_tr_b16 v[252:253], v203
	v_mfma_f32_16x16x32_bf16 v[144:147], v[230:233], v[128:131], v[144:147]
	s_nop 0
	s_nop 0
	s_nop 0
	v_pk_mul_f32 v[140:141], v[140:141], v[142:143] op_sel_hi:[1,0]
	s_waitcnt vmcnt(21)
	s_cmpk_lt_i32 s48, 0x2e0
	s_cbranch_scc1 .LE28_b
	s_waitcnt vmcnt(1)
.LE28_b:
	v_lshlrev_b32_e32 v143, 16, v112
	s_nop 0
	ds_read_b64_tr_b16 v[228:229], v197 offset:8
	ds_read_b64_tr_b16 v[226:227], v196 offset:8
	v_mfma_f32_16x16x32_bf16 v[144:147], v[234:237], v[132:135], v[144:147]
	s_nop 0
	s_nop 0
	s_nop 0
	v_lshlrev_b32_e32 v142, 16, v108
	v_mul_f32_e32 v138, v137, v136
	s_nop 0
	ds_read_b64_tr_b16 v[232:233], v198 offset:8
	ds_read_b64_tr_b16 v[230:231], v196 offset:8200
	s_waitcnt lgkmcnt(6)
	v_mfma_f32_16x16x32_bf16 v[144:147], v[246:249], v[120:123], v[144:147]
	s_nop 0
	s_nop 0
	s_nop 0
	v_pk_mul_f32 v[142:143], v[140:141], v[142:143]
	v_lshlrev_b64 v[136:137], 11, v[166:167]
	s_nop 0
	ds_read_b64_tr_b16 v[236:237], v199 offset:8
	ds_read_b64_tr_b16 v[234:235], v196 offset:16392
	s_waitcnt lgkmcnt(6)
	v_mfma_f32_16x16x32_bf16 v[144:147], v[250:253], v[116:119], v[144:147]
	s_nop 0
	v_lshl_add_u64 v[136:137], s[18:19], 0, v[136:137]
	v_lshl_add_u64 v[136:137], v[136:137], 0, v[200:201]
	ds_read_b64_tr_b16 v[248:249], v202 offset:8
	ds_read_b64_tr_b16 v[246:247], v196 offset:24584
	s_waitcnt lgkmcnt(6)
	v_mfma_f32_16x16x32_bf16 v[148:151], v[226:229], v[124:127], 0
	s_nop 3
	v_mul_f32_e64 v146, v146, v138
	v_mul_f32_e64 v147, v147, v138
	v_pk_mul_f32 v[144:145], v[144:145], v[138:139] op_sel_hi:[1,0]
	s_add_i32 s43, s43, 32
	s_nop 0
	ds_read_b64_tr_b16 v[252:253], v203 offset:8
	ds_read_b64_tr_b16 v[250:251], v196 offset:32776
	s_waitcnt lgkmcnt(6)
	v_mfma_f32_16x16x32_bf16 v[148:151], v[230:233], v[128:131], v[148:151]
	s_nop 0
	s_cmpk_lt_i32 s48, 0x2e0
	s_nop 0
	ds_read_b64_tr_b16 v[228:229], v205
	ds_read_b64_tr_b16 v[226:227], v204
	s_waitcnt lgkmcnt(6)
	v_mfma_f32_16x16x32_bf16 v[148:151], v[234:237], v[132:135], v[148:151]
	s_nop 0
	s_nop 0
	ds_read_b64_tr_b16 v[230:231], v204 offset:8192
	ds_read_b64_tr_b16 v[232:233], v206
	s_waitcnt lgkmcnt(6)
	v_mfma_f32_16x16x32_bf16 v[148:151], v[246:249], v[120:123], v[148:151]
	s_nop 0
	s_nop 0
	ds_read_b64_tr_b16 v[234:235], v204 offset:16384
	ds_read_b64_tr_b16 v[236:237], v207
	s_waitcnt lgkmcnt(6)
	v_mfma_f32_16x16x32_bf16 v[148:151], v[250:253], v[116:119], v[148:151]
	s_nop 7
	v_pk_mul_f32 v[150:151], v[150:151], v[138:139] op_sel_hi:[1,0]
	v_pk_mul_f32 v[148:149], v[148:149], v[138:139] op_sel_hi:[1,0]
	v_add_f32_e32 v139, v142, v143
	v_and_b32_e32 v143, 0xffff0000, v112
	v_and_b32_e32 v142, 0xffff0000, v108
	v_pk_mul_f32 v[142:143], v[140:141], v[142:143]
	v_add_f32_e32 v139, v139, v144
	v_add_f32_e32 v108, v142, v143
	v_lshlrev_b32_e32 v143, 16, v113
	v_lshlrev_b32_e32 v142, 16, v109
	v_pk_mul_f32 v[142:143], v[140:141], v[142:143]
	v_add_f32_e32 v108, v108, v145
	v_add_f32_e32 v112, v142, v143
	v_cvt_pk_bf16_f32 v108, v139, v108
	v_add_f32_e32 v139, v112, v146
	v_and_b32_e32 v113, 0xffff0000, v113
	v_and_b32_e32 v112, 0xffff0000, v109
	v_pk_mul_f32 v[112:113], v[140:141], v[112:113]
	s_nop 0
	v_add_f32_e32 v109, v112, v113
	v_lshlrev_b32_e32 v113, 16, v114
	v_lshlrev_b32_e32 v112, 16, v110
	v_pk_mul_f32 v[112:113], v[140:141], v[112:113]
	v_add_f32_e32 v109, v109, v147
	v_add_f32_e32 v112, v112, v113
	v_cvt_pk_bf16_f32 v109, v139, v109
	v_add_f32_e32 v139, v112, v148
	v_and_b32_e32 v113, 0xffff0000, v114
	v_and_b32_e32 v112, 0xffff0000, v110
	v_pk_mul_f32 v[112:113], v[140:141], v[112:113]
	s_nop 0
	v_add_f32_e32 v110, v112, v113
	v_lshlrev_b32_e32 v113, 16, v115
	v_lshlrev_b32_e32 v112, 16, v111
	v_pk_mul_f32 v[112:113], v[140:141], v[112:113]
	v_add_f32_e32 v110, v110, v149
	v_add_f32_e32 v112, v112, v113
	v_add_f32_e32 v114, v112, v150
	v_and_b32_e32 v113, 0xffff0000, v115
	v_and_b32_e32 v112, 0xffff0000, v111
	v_pk_mul_f32 v[112:113], v[140:141], v[112:113]
	v_cvt_pk_bf16_f32 v110, v139, v110
	s_nop 0
	v_add_f32_e32 v111, v112, v113
	v_add_f32_e32 v111, v111, v151
	v_cvt_pk_bf16_f32 v111, v114, v111
	global_store_dwordx4 v[136:137], v[108:111], off
	s_nop 0
	s_nop 0
	s_nop 0
	s_nop 0
	s_nop 0
	ds_read_b64_tr_b16 v[246:247], v204 offset:24576
	ds_read_b64_tr_b16 v[248:249], v212
	s_waitcnt lgkmcnt(6)
	v_mfma_f32_16x16x32_bf16 v[108:111], v[226:229], v[124:127], 0
	s_nop 0
	s_nop 0
	s_nop 0
	s_nop 0
	ds_read_b64_tr_b16 v[250:251], v204 offset:32768
	ds_read_b64_tr_b16 v[252:253], v213
	s_waitcnt lgkmcnt(6)
	v_mfma_f32_16x16x32_bf16 v[108:111], v[230:233], v[128:131], v[108:111]
	s_nop 0
	s_nop 0
	s_nop 0
	s_nop 0
	ds_read_b64_tr_b16 v[228:229], v205 offset:8
	ds_read_b64_tr_b16 v[226:227], v204 offset:8
	s_waitcnt lgkmcnt(6)
	v_mfma_f32_16x16x32_bf16 v[108:111], v[234:237], v[132:135], v[108:111]
	s_nop 0
	s_nop 0
	s_nop 0
	s_nop 0
	ds_read_b64_tr_b16 v[232:233], v206 offset:8
	ds_read_b64_tr_b16 v[230:231], v204 offset:8200
	s_waitcnt lgkmcnt(6)
	v_mfma_f32_16x16x32_bf16 v[108:111], v[246:249], v[120:123], v[108:111]
	s_nop 0
	s_nop 0
	s_nop 0
	s_nop 0
	ds_read_b64_tr_b16 v[236:237], v207 offset:8
	ds_read_b64_tr_b16 v[234:235], v204 offset:16392
	s_waitcnt lgkmcnt(6)
	v_mfma_f32_16x16x32_bf16 v[108:111], v[250:253], v[116:119], v[108:111]
	s_nop 0
	v_lshlrev_b32_e32 v143, 16, v104
	v_lshlrev_b32_e32 v142, 16, v100
	ds_read_b64_tr_b16 v[248:249], v212 offset:8
	ds_read_b64_tr_b16 v[246:247], v204 offset:24584
	s_waitcnt lgkmcnt(6)
	v_mfma_f32_16x16x32_bf16 v[112:115], v[226:229], v[124:127], 0
	v_mul_f32_e64 v142, v140, v142
	v_mul_f32_e64 v143, v141, v143
	s_nop 1
	v_pk_mul_f32 v[110:111], v[110:111], v[138:139] op_sel_hi:[1,0]
	v_pk_mul_f32 v[108:109], v[108:109], v[138:139] op_sel_hi:[1,0]
	s_nop 0
	ds_read_b64_tr_b16 v[252:253], v213 offset:8
	ds_read_b64_tr_b16 v[250:251], v204 offset:32776
	s_waitcnt lgkmcnt(6)
	v_mfma_f32_16x16x32_bf16 v[112:115], v[230:233], v[128:131], v[112:115]
	s_nop 0
	s_nop 0
	ds_read_b64_tr_b16 v[228:229], v215
	ds_read_b64_tr_b16 v[226:227], v214
	s_waitcnt lgkmcnt(6)
	v_mfma_f32_16x16x32_bf16 v[112:115], v[234:237], v[132:135], v[112:115]
	s_nop 0
	s_nop 0
	ds_read_b64_tr_b16 v[230:231], v214 offset:8192
	ds_read_b64_tr_b16 v[232:233], v216
	s_waitcnt lgkmcnt(6)
	v_mfma_f32_16x16x32_bf16 v[112:115], v[246:249], v[120:123], v[112:115]
	s_nop 0
	s_nop 0
	ds_read_b64_tr_b16 v[234:235], v214 offset:16384
	ds_read_b64_tr_b16 v[236:237], v217
	s_waitcnt lgkmcnt(6)
	v_mfma_f32_16x16x32_bf16 v[112:115], v[250:253], v[116:119], v[112:115]
	s_nop 7
	v_pk_mul_f32 v[114:115], v[114:115], v[138:139] op_sel_hi:[1,0]
	v_pk_mul_f32 v[112:113], v[112:113], v[138:139] op_sel_hi:[1,0]
	v_add_f32_e32 v139, v142, v143
	v_and_b32_e32 v143, 0xffff0000, v104
	v_and_b32_e32 v142, 0xffff0000, v100
	v_pk_mul_f32 v[142:143], v[140:141], v[142:143]
	v_add_f32_e32 v108, v139, v108
	v_add_f32_e32 v100, v142, v143
	v_add_f32_e32 v100, v100, v109
	v_cvt_pk_bf16_f32 v100, v108, v100
	v_lshlrev_b32_e32 v109, 16, v105
	v_lshlrev_b32_e32 v108, 16, v101
	v_pk_mul_f32 v[108:109], v[140:141], v[108:109]
	v_and_b32_e32 v105, 0xffff0000, v105
	v_add_f32_e32 v104, v108, v109
	v_add_f32_e32 v108, v104, v110
	v_and_b32_e32 v104, 0xffff0000, v101
	v_pk_mul_f32 v[104:105], v[140:141], v[104:105]
	s_nop 0
	v_add_f32_e32 v101, v104, v105
	v_lshlrev_b32_e32 v105, 16, v106
	v_lshlrev_b32_e32 v104, 16, v102
	v_pk_mul_f32 v[104:105], v[140:141], v[104:105]
	v_add_f32_e32 v101, v101, v111
	v_add_f32_e32 v104, v104, v105
	v_cvt_pk_bf16_f32 v101, v108, v101
	v_add_f32_e32 v108, v104, v112
	v_and_b32_e32 v105, 0xffff0000, v106
	v_and_b32_e32 v104, 0xffff0000, v102
	v_pk_mul_f32 v[104:105], v[140:141], v[104:105]
	s_nop 0
	v_add_f32_e32 v102, v104, v105
	v_lshlrev_b32_e32 v105, 16, v107
	v_lshlrev_b32_e32 v104, 16, v103
	v_pk_mul_f32 v[104:105], v[140:141], v[104:105]
	v_add_f32_e32 v102, v102, v113
	v_add_f32_e32 v104, v104, v105
	v_add_f32_e32 v106, v104, v114
	v_and_b32_e32 v105, 0xffff0000, v107
	v_and_b32_e32 v104, 0xffff0000, v103
	v_pk_mul_f32 v[104:105], v[140:141], v[104:105]
	v_cvt_pk_bf16_f32 v102, v108, v102
	s_nop 0
	v_add_f32_e32 v103, v104, v105
	v_add_f32_e32 v103, v103, v115
	v_cvt_pk_bf16_f32 v103, v106, v103
	global_store_dwordx4 v[136:137], v[100:103], off offset:64
	s_nop 0
	s_nop 0
	s_nop 0
	s_nop 0
	s_nop 0
	ds_read_b64_tr_b16 v[246:247], v214 offset:24576
	ds_read_b64_tr_b16 v[248:249], v218
	s_waitcnt lgkmcnt(6)
	v_mfma_f32_16x16x32_bf16 v[100:103], v[226:229], v[124:127], 0
	s_nop 0
	s_nop 0
	s_nop 0
	s_nop 0
	ds_read_b64_tr_b16 v[250:251], v214 offset:32768
	ds_read_b64_tr_b16 v[252:253], v219
	s_waitcnt lgkmcnt(6)
	v_mfma_f32_16x16x32_bf16 v[100:103], v[230:233], v[128:131], v[100:103]
	s_nop 0
	s_nop 0
	s_nop 0
	s_nop 0
	ds_read_b64_tr_b16 v[228:229], v215 offset:8
	ds_read_b64_tr_b16 v[226:227], v214 offset:8
	s_waitcnt lgkmcnt(6)
	v_mfma_f32_16x16x32_bf16 v[100:103], v[234:237], v[132:135], v[100:103]
	s_nop 0
	s_nop 0
	s_nop 0
	s_nop 0
	ds_read_b64_tr_b16 v[232:233], v216 offset:8
	ds_read_b64_tr_b16 v[230:231], v214 offset:8200
	s_waitcnt lgkmcnt(6)
	v_mfma_f32_16x16x32_bf16 v[100:103], v[246:249], v[120:123], v[100:103]
	s_nop 0
	s_nop 0
	s_nop 0
	s_nop 0
	s_nop 0
	ds_read_b64_tr_b16 v[236:237], v217 offset:8
	ds_read_b64_tr_b16 v[234:235], v214 offset:16392
	s_waitcnt lgkmcnt(6)
	v_mfma_f32_16x16x32_bf16 v[100:103], v[250:253], v[116:119], v[100:103]
	s_nop 0
	v_lshlrev_b32_e32 v109, 16, v80
	v_lshlrev_b32_e32 v108, 16, v76
	ds_read_b64_tr_b16 v[248:249], v218 offset:8
	ds_read_b64_tr_b16 v[246:247], v214 offset:24584
	s_waitcnt lgkmcnt(6)
	v_mfma_f32_16x16x32_bf16 v[104:107], v[226:229], v[124:127], 0
	v_mul_f32_e64 v108, v140, v108
	v_mul_f32_e64 v109, v141, v109
	s_nop 1
	v_pk_mul_f32 v[100:101], v[138:139], v[100:101] op_sel_hi:[0,1]
	v_add_f32_e32 v108, v108, v109
	s_nop 0
	ds_read_b64_tr_b16 v[252:253], v219 offset:8
	ds_read_b64_tr_b16 v[250:251], v214 offset:32776
	s_waitcnt lgkmcnt(6)
	v_mfma_f32_16x16x32_bf16 v[104:107], v[230:233], v[128:131], v[104:107]
	s_nop 0
	v_add_f32_e32 v100, v108, v100
	v_and_b32_e32 v109, 0xffff0000, v80
	s_nop 0
	ds_read_b64_tr_b16 v[228:229], v221
	ds_read_b64_tr_b16 v[226:227], v220
	s_waitcnt lgkmcnt(6)
	v_mfma_f32_16x16x32_bf16 v[104:107], v[234:237], v[132:135], v[104:107]
	v_and_b32_e32 v108, 0xffff0000, v76
	v_pk_mul_f32 v[108:109], v[140:141], v[108:109]
	v_pk_mul_f32 v[102:103], v[138:139], v[102:103] op_sel_hi:[0,1]
	ds_read_b64_tr_b16 v[230:231], v220 offset:8192
	ds_read_b64_tr_b16 v[232:233], v222
	s_waitcnt lgkmcnt(6)
	v_mfma_f32_16x16x32_bf16 v[104:107], v[246:249], v[120:123], v[104:107]
	s_nop 0
	v_add_f32_e32 v76, v108, v109
	v_add_f32_e32 v76, v76, v101
	v_cvt_pk_bf16_f32 v76, v100, v76
	v_lshlrev_b32_e32 v101, 16, v81
	v_lshlrev_b32_e32 v100, 16, v77
	v_pk_mul_f32 v[100:101], v[140:141], v[100:101]
	s_nop 0
	ds_read_b64_tr_b16 v[234:235], v220 offset:16384
	ds_read_b64_tr_b16 v[236:237], v223
	s_waitcnt lgkmcnt(6)
	v_mfma_f32_16x16x32_bf16 v[104:107], v[250:253], v[116:119], v[104:107]
	v_add_f32_e32 v80, v100, v101
	v_add_f32_e32 v100, v80, v102
	v_and_b32_e32 v81, 0xffff0000, v81
	v_and_b32_e32 v80, 0xffff0000, v77
	v_pk_mul_f32 v[80:81], v[140:141], v[80:81]
	s_nop 2
	v_pk_mul_f32 v[104:105], v[138:139], v[104:105] op_sel_hi:[0,1]
	v_add_f32_e32 v77, v80, v81
	v_lshlrev_b32_e32 v81, 16, v82
	v_lshlrev_b32_e32 v80, 16, v78
	v_pk_mul_f32 v[80:81], v[140:141], v[80:81]
	v_add_f32_e32 v77, v77, v103
	v_add_f32_e32 v80, v80, v81
	v_cvt_pk_bf16_f32 v77, v100, v77
	v_add_f32_e32 v100, v80, v104
	v_and_b32_e32 v81, 0xffff0000, v82
	v_and_b32_e32 v80, 0xffff0000, v78
	v_pk_mul_f32 v[80:81], v[140:141], v[80:81]
	v_pk_mul_f32 v[106:107], v[138:139], v[106:107] op_sel_hi:[0,1]
	v_add_f32_e32 v78, v80, v81
	v_lshlrev_b32_e32 v81, 16, v83
	v_lshlrev_b32_e32 v80, 16, v79
	v_pk_mul_f32 v[80:81], v[140:141], v[80:81]
	v_add_f32_e32 v78, v78, v105
	v_add_f32_e32 v80, v80, v81
	v_add_f32_e32 v82, v80, v106
	v_and_b32_e32 v81, 0xffff0000, v83
	v_and_b32_e32 v80, 0xffff0000, v79
	v_pk_mul_f32 v[80:81], v[140:141], v[80:81]
	v_cvt_pk_bf16_f32 v78, v100, v78
	s_nop 0
	v_add_f32_e32 v79, v80, v81
	v_add_f32_e32 v79, v79, v107
	v_cvt_pk_bf16_f32 v79, v82, v79
	global_store_dwordx4 v[136:137], v[76:79], off offset:128
	s_nop 0
	s_nop 0
	s_nop 0
	s_nop 0
	s_nop 0
	ds_read_b64_tr_b16 v[246:247], v220 offset:24576
	ds_read_b64_tr_b16 v[248:249], v224
	s_waitcnt lgkmcnt(6)
	v_mfma_f32_16x16x32_bf16 v[76:79], v[226:229], v[124:127], 0
	s_nop 0
	s_nop 0
	s_nop 0
	s_nop 0
	ds_read_b64_tr_b16 v[250:251], v220 offset:32768
	ds_read_b64_tr_b16 v[252:253], v225
	s_waitcnt lgkmcnt(6)
	v_mfma_f32_16x16x32_bf16 v[76:79], v[230:233], v[128:131], v[76:79]
	s_nop 0
	s_nop 0
	s_nop 0
	s_nop 0
	ds_read_b64_tr_b16 v[228:229], v221 offset:8
	ds_read_b64_tr_b16 v[226:227], v220 offset:8
	s_waitcnt lgkmcnt(6)
	v_mfma_f32_16x16x32_bf16 v[76:79], v[234:237], v[132:135], v[76:79]
	s_nop 0
	s_nop 0
	s_nop 0
	s_nop 0
	ds_read_b64_tr_b16 v[232:233], v222 offset:8
	ds_read_b64_tr_b16 v[230:231], v220 offset:8200
	s_waitcnt lgkmcnt(6)
	v_mfma_f32_16x16x32_bf16 v[76:79], v[246:249], v[120:123], v[76:79]
	s_nop 0
	s_nop 0
	s_nop 0
	s_nop 0
	ds_read_b64_tr_b16 v[236:237], v223 offset:8
	ds_read_b64_tr_b16 v[234:235], v220 offset:16392
	s_waitcnt lgkmcnt(6)
	v_mfma_f32_16x16x32_bf16 v[76:79], v[250:253], v[116:119], v[76:79]
	s_nop 0
	s_waitcnt vmcnt(23)
	s_cbranch_scc1 .LE28_c
	s_waitcnt vmcnt(3)
.LE28_c:
	v_lshlrev_b32_e32 v101, 16, v72
	v_lshlrev_b32_e32 v100, 16, v68
	ds_read_b64_tr_b16 v[248:249], v224 offset:8
	ds_read_b64_tr_b16 v[246:247], v220 offset:24584
	s_waitcnt lgkmcnt(6)
	v_mfma_f32_16x16x32_bf16 v[80:83], v[226:229], v[124:127], 0
	v_mul_f32_e64 v100, v140, v100
	v_mul_f32_e64 v101, v141, v101
	s_nop 0
	v_pk_mul_f32 v[76:77], v[138:139], v[76:77] op_sel_hi:[0,1]
	v_add_f32_e32 v100, v100, v101
	s_nop 0
	ds_read_b64_tr_b16 v[252:253], v225 offset:8
	ds_read_b64_tr_b16 v[250:251], v220 offset:32776
	s_waitcnt lgkmcnt(6)
	v_mfma_f32_16x16x32_bf16 v[80:83], v[230:233], v[128:131], v[80:83]
	s_nop 0
	v_add_f32_e32 v76, v100, v76
	v_and_b32_e32 v101, 0xffff0000, v72
	s_nop 0
	s_waitcnt lgkmcnt(4)
	v_mfma_f32_16x16x32_bf16 v[80:83], v[234:237], v[132:135], v[80:83]
	s_nop 0
	v_and_b32_e32 v100, 0xffff0000, v68
	v_pk_mul_f32 v[100:101], v[140:141], v[100:101]
	s_nop 0
	s_waitcnt lgkmcnt(2)
	v_mfma_f32_16x16x32_bf16 v[80:83], v[246:249], v[120:123], v[80:83]
	s_nop 0
	v_add_f32_e32 v68, v100, v101
	v_add_f32_e32 v68, v68, v77
	v_cvt_pk_bf16_f32 v68, v76, v68
	v_lshlrev_b32_e32 v77, 16, v73
	v_lshlrev_b32_e32 v76, 16, v69
	v_pk_mul_f32 v[76:77], v[140:141], v[76:77]
	v_pk_mul_f32 v[78:79], v[138:139], v[78:79] op_sel_hi:[0,1]
	v_add_f32_e32 v72, v76, v77
	s_nop 0
	s_waitcnt lgkmcnt(0)
	v_mfma_f32_16x16x32_bf16 v[80:83], v[250:253], v[116:119], v[80:83]
	v_add_f32_e32 v76, v72, v78
	v_and_b32_e32 v73, 0xffff0000, v73
	v_and_b32_e32 v72, 0xffff0000, v69
	v_pk_mul_f32 v[72:73], v[140:141], v[72:73]
	s_waitcnt vmcnt(3)
	v_mov_b64_e32 v[122:123], v[98:99]
	v_add_f32_e32 v69, v72, v73
	v_lshlrev_b32_e32 v73, 16, v74
	v_lshlrev_b32_e32 v72, 16, v70
	v_pk_mul_f32 v[72:73], v[140:141], v[72:73]
	v_pk_mul_f32 v[80:81], v[138:139], v[80:81] op_sel_hi:[0,1]
	v_add_f32_e32 v69, v69, v79
	v_add_f32_e32 v72, v72, v73
	v_cvt_pk_bf16_f32 v69, v76, v69
	v_add_f32_e32 v76, v72, v80
	v_and_b32_e32 v73, 0xffff0000, v74
	v_and_b32_e32 v72, 0xffff0000, v70
	v_pk_mul_f32 v[72:73], v[140:141], v[72:73]
	v_pk_mul_f32 v[82:83], v[138:139], v[82:83] op_sel_hi:[0,1]
	v_add_f32_e32 v70, v72, v73
	v_lshlrev_b32_e32 v73, 16, v75
	v_lshlrev_b32_e32 v72, 16, v71
	v_pk_mul_f32 v[72:73], v[140:141], v[72:73]
	v_add_f32_e32 v70, v70, v81
	v_add_f32_e32 v72, v72, v73
	v_add_f32_e32 v74, v72, v82
	v_and_b32_e32 v73, 0xffff0000, v75
	v_and_b32_e32 v72, 0xffff0000, v71
	v_pk_mul_f32 v[72:73], v[140:141], v[72:73]
	v_cvt_pk_bf16_f32 v70, v76, v70
	v_mov_b64_e32 v[126:127], v[94:95]
	v_add_f32_e32 v71, v72, v73
	v_add_f32_e32 v71, v71, v83
	v_cvt_pk_bf16_f32 v71, v74, v71
	global_store_dwordx4 v[136:137], v[68:71], off offset:192
	s_nop 0
	s_barrier
	v_mov_b64_e32 v[130:131], v[86:87]
	v_mov_b64_e32 v[118:119], v[90:91]
	v_mov_b64_e32 v[120:121], v[96:97]
	v_mov_b64_e32 v[124:125], v[92:93]
	v_mov_b64_e32 v[128:129], v[84:85]
	v_mov_b64_e32 v[116:117], v[88:89]
	s_cbranch_scc0 .LBB0_548

.LBB0_524:
	s_lshl_b32 s50, s49, 7
	v_add_u32_e32 v226, s50, v170
	s_bfe_u32 s53, s48, 0x30003
	s_lshl_b64 s[18:19], s[56:57], s18
	v_or_b32_e32 v68, v226, v168
	s_add_u32 s18, s18, s28
	v_ashrrev_i32_e32 v69, 31, v68
	s_addc_u32 s19, s19, 0
	v_lshlrev_b64 v[68:69], s51, v[68:69]
	v_lshl_add_u64 v[166:167], s[18:19], 0, v[68:69]
	v_mov_b64_e32 v[68:69], s[24:25]
	v_mad_u64_u32 v[68:69], s[18:19], v166, s82, v[68:69]
	v_mov_b32_e32 v70, v69
	v_mad_u64_u32 v[70:71], s[18:19], v167, s82, v[70:71]
	v_mov_b32_e32 v69, v70
	s_lshl_b32 s56, s53, 2
	v_lshl_add_u64 v[68:69], v[68:69], 0, s[56:57]
	global_load_dword v209, v[68:69], off
	global_load_dword v208, v[68:69], off offset:32
	v_mov_b64_e32 v[68:69], s[22:23]
	v_mad_u64_u32 v[68:69], s[18:19], v166, s88, v[68:69]
	v_mov_b32_e32 v70, v69
	v_mad_u64_u32 v[70:71], s[18:19], v167, s88, v[70:71]
	v_mov_b32_e32 v69, v70
	s_lshl_b32 s56, s53, 8
	v_lshl_add_u64 v[68:69], v[68:69], 0, s[56:57]
	v_lshl_add_u64 v[68:69], v[68:69], 0, v[200:201]
	s_mov_b64 s[18:19], 0x1800
	v_lshl_add_u64 v[72:73], v[68:69], 0, s[18:19]
	s_movk_i32 s18, 0x1000
	v_add_co_u32_e32 v74, vcc, s18, v68
	v_add_u32_e32 v84, 0, v176
	s_nop 0
	v_addc_co_u32_e32 v75, vcc, 0, v69, vcc
	global_load_dwordx4 v[108:111], v[68:69], off
	global_load_dwordx4 v[100:103], v[68:69], off offset:64
	global_load_dwordx4 v[104:107], v[72:73], off offset:64
	global_load_dwordx4 v[80:83], v[72:73], off offset:128
	global_load_dwordx4 v[76:79], v[68:69], off offset:128
	s_nop 0
	global_load_dwordx4 v[68:71], v[68:69], off offset:192
	s_nop 0
	global_load_dwordx4 v[112:115], v[74:75], off offset:2048
	s_nop 0
	global_load_dwordx4 v[72:75], v[72:73], off offset:192
	s_waitcnt vmcnt(15)
	ds_write_b128 v84, v[4:7]
	v_add_u32_e32 v84, s42, v176
	s_waitcnt vmcnt(14)
	ds_write_b128 v84, v[8:11]
	v_add_u32_e32 v84, 0, v177
	ds_write_b128 v84, v[12:15]
	v_add_u32_e32 v84, s42, v177
	ds_write_b128 v84, v[16:19]
	v_add_u32_e32 v84, 0, v178
	ds_write_b128 v84, v[20:23]
	v_add_u32_e32 v84, s42, v178
	ds_write_b128 v84, v[24:27]
	v_add_u32_e32 v84, 0, v179
	ds_write_b128 v84, v[28:31]
	v_add_u32_e32 v84, s42, v179
	ds_write_b128 v84, v[32:35]
	v_add_u32_e32 v84, 0, v180
	ds_write_b128 v84, v[40:43]
	v_add_u32_e32 v84, s42, v180
	ds_write_b128 v84, v[44:47]
	v_add_u32_e32 v84, 0, v181
	ds_write_b128 v84, v[48:51]
	v_add_u32_e32 v84, s42, v181
	ds_write_b128 v84, v[52:55]
	v_add_u32_e32 v84, 0, v182
	ds_write_b128 v84, v[56:59]
	v_add_u32_e32 v84, s42, v182
	ds_write_b128 v84, v[60:63]
	v_add_u32_e32 v84, 0, v183
	ds_write_b128 v84, v[64:67]
	v_add_u32_e32 v84, s42, v183
	ds_write_b128 v84, v[36:39]
	s_waitcnt lgkmcnt(0)
	s_barrier
	s_waitcnt vmcnt(14)
	v_mov_b64_e32 v[88:89], v[116:117]
	v_mov_b64_e32 v[84:85], v[128:129]
	v_mov_b64_e32 v[92:93], v[124:125]
	v_mov_b64_e32 v[96:97], v[120:121]
	s_cmpk_gt_i32 s48, 0x2df
	v_mov_b64_e32 v[90:91], v[118:119]
	v_mov_b64_e32 v[86:87], v[130:131]
	v_mov_b64_e32 v[94:95], v[126:127]
	v_mov_b64_e32 v[98:99], v[122:123]
	s_cbranch_scc1 .LBB0_546
	s_lshr_b32 s28, s43, 3
	s_ashr_i32 s29, s43, 8
	s_and_b32 s18, s28, 24
	s_or_b32 s31, s18, s39
	s_lshl_b32 s61, s29, 1
	s_mov_b64 s[18:19], -1
	s_and_b64 vcc, exec, s[20:21]
	s_cbranch_vccz .LBB0_527
	s_sub_i32 s18, 5, s61
	s_lshr_b32 s30, s31, s18
	s_lshl_b32 s19, s35, s18
	s_lshl_b32 s18, -1, s18
	s_andn2_b32 s18, s31, s18
	s_add_i32 s62, s18, s19
	s_mov_b64 s[18:19], 0

.LBB0_529:
	s_lshr_b32 s63, s33, s61
	s_lshl_b32 s62, s62, 7
	s_lshl_b64 s[18:19], s[56:57], s26
	s_add_u32 s26, s18, s30
	s_mul_i32 s18, s29, 0xc00
	s_addc_u32 s27, s19, 0
	s_ashr_i32 s19, s18, 31
	s_lshl_b64 s[18:19], s[18:19], 1
	s_add_u32 s18, s22, s18
	s_addc_u32 s19, s23, s19
	s_lshl_b32 s28, s28, 8
	v_add_u32_e32 v36, s62, v171
	s_and_b32 s28, s28, 0x700
	s_add_u32 s28, s18, s28
	v_ashrrev_i32_e32 v37, 31, v36
	s_addc_u32 s29, s19, 0
	v_lshlrev_b64 v[4:5], s61, v[36:37]
	v_lshl_add_u64 v[4:5], s[26:27], 0, v[4:5]
	v_mov_b64_e32 v[6:7], s[28:29]
	v_mad_u64_u32 v[6:7], s[18:19], v4, s88, v[6:7]
	v_mov_b32_e32 v4, v7
	v_mad_u64_u32 v[4:5], s[18:19], v5, s88, v[4:5]
	v_mov_b32_e32 v7, v4
	v_mov_b32_e32 v165, v201
	v_lshl_add_u64 v[84:85], v[6:7], 0, v[164:165]
	v_cmp_lt_i32_e32 vcc, -1, v36
	v_cmp_gt_i32_e64 s[18:19], s63, v36
	v_mov_b64_e32 v[10:11], v[2:3]
	v_mov_b64_e32 v[6:7], v[2:3]
	s_and_b64 s[30:31], vcc, s[18:19]
	v_mov_b64_e32 v[8:9], v[0:1]
	v_mov_b64_e32 v[4:5], v[0:1]
	s_and_saveexec_b64 s[18:19], s[30:31]
	s_nop 0
	v_lshl_add_u64 v[8:9], v[84:85], 0, s[92:93]
	global_load_dwordx4 v[4:7], v[84:85], off offset:2048
	s_nop 0
	global_load_dwordx4 v[8:11], v[8:9], off offset:2048
.LBB0_531:
	s_or_b64 exec, exec, s[18:19]
	v_add_u32_e32 v12, 32, v36
	s_movk_i32 s18, 0xffdf
	v_cmp_lt_i32_e32 vcc, s18, v36
	v_cmp_gt_i32_e64 s[18:19], s63, v12
	v_mov_b64_e32 v[18:19], v[2:3]
	v_mov_b64_e32 v[14:15], v[2:3]
	s_lshl_b64 s[30:31], 0x48000, s61
	s_and_b64 s[66:67], vcc, s[18:19]
	v_mov_b64_e32 v[16:17], v[0:1]
	v_mov_b64_e32 v[12:13], v[0:1]
	s_and_saveexec_b64 s[18:19], s[66:67]
	s_nop 0
	v_lshl_add_u64 v[12:13], s[30:31], 1, v[84:85]
	v_lshl_add_u64 v[16:17], v[12:13], 0, s[92:93]
	global_load_dwordx4 v[12:15], v[12:13], off offset:2048
	s_nop 0
	global_load_dwordx4 v[16:19], v[16:17], off offset:2048
.LBB0_533:
	s_or_b64 exec, exec, s[18:19]
	v_add_u32_e32 v20, s62, v169
	v_cmp_lt_i32_e32 vcc, -1, v20
	v_cmp_gt_i32_e64 s[18:19], s63, v20
	v_mov_b64_e32 v[26:27], v[2:3]
	v_mov_b64_e32 v[22:23], v[2:3]
	s_and_b64 s[66:67], vcc, s[18:19]
	v_mov_b64_e32 v[24:25], v[0:1]
	v_mov_b64_e32 v[20:21], v[0:1]
	s_and_saveexec_b64 s[18:19], s[66:67]
	s_nop 0
	s_lshl_b64 s[66:67], 0x90000, s61
	v_lshl_add_u64 v[20:21], s[66:67], 1, v[84:85]
	v_lshl_add_u64 v[24:25], v[20:21], 0, s[92:93]
	global_load_dwordx4 v[20:23], v[20:21], off offset:2048
	s_nop 0
	global_load_dwordx4 v[24:27], v[24:25], off offset:2048
.LBB0_535:
	s_or_b64 exec, exec, s[18:19]
	v_add_u32_e32 v28, 0x60, v36
	s_movk_i32 s18, 0xff9f
	v_cmp_lt_i32_e32 vcc, s18, v36
	v_cmp_gt_i32_e64 s[18:19], s63, v28
	v_mov_b64_e32 v[34:35], v[2:3]
	v_mov_b64_e32 v[30:31], v[2:3]
	s_and_b64 s[66:67], vcc, s[18:19]
	v_mov_b64_e32 v[32:33], v[0:1]
	v_mov_b64_e32 v[28:29], v[0:1]
	s_and_saveexec_b64 s[18:19], s[66:67]
	s_nop 0
	v_mad_u64_u32 v[28:29], s[66:67], s30, 6, v[84:85]
	v_mov_b32_e32 v30, v29
	v_mad_u64_u32 v[30:31], s[66:67], s31, 6, v[30:31]
	v_mov_b32_e32 v29, v30
	v_lshl_add_u64 v[32:33], v[28:29], 0, s[92:93]
	global_load_dwordx4 v[28:31], v[28:29], off offset:2048
	s_nop 0
	global_load_dwordx4 v[32:35], v[32:33], off offset:2048
.LBB0_537:
	s_or_b64 exec, exec, s[18:19]
	v_add_u32_e32 v37, 0x80, v36
	s_movk_i32 s18, 0xff7f
	v_cmp_lt_i32_e32 vcc, s18, v36
	v_cmp_gt_i32_e64 s[18:19], s63, v37
	v_mov_b64_e32 v[46:47], v[2:3]
	v_mov_b64_e32 v[42:43], v[2:3]
	s_and_b64 s[66:67], vcc, s[18:19]
	v_mov_b64_e32 v[44:45], v[0:1]
	v_mov_b64_e32 v[40:41], v[0:1]
	s_and_saveexec_b64 s[18:19], s[66:67]
	s_nop 0
	s_lshl_b64 s[66:67], 0x120000, s61
	v_lshl_add_u64 v[38:39], s[66:67], 1, v[84:85]
	v_lshl_add_u64 v[44:45], v[38:39], 0, s[92:93]
	global_load_dwordx4 v[40:43], v[38:39], off offset:2048
	s_nop 0
	global_load_dwordx4 v[44:47], v[44:45], off offset:2048
.LBB0_539:
	s_or_b64 exec, exec, s[18:19]
	v_add_u32_e32 v37, 0xa0, v36
	s_movk_i32 s18, 0xff5f
	v_cmp_lt_i32_e32 vcc, s18, v36
	v_cmp_gt_i32_e64 s[18:19], s63, v37
	v_mov_b64_e32 v[54:55], v[2:3]
	v_mov_b64_e32 v[50:51], v[2:3]
	s_and_b64 s[66:67], vcc, s[18:19]
	v_mov_b64_e32 v[52:53], v[0:1]
	v_mov_b64_e32 v[48:49], v[0:1]
	s_and_saveexec_b64 s[18:19], s[66:67]
	s_nop 0
	v_mad_u64_u32 v[38:39], s[66:67], s30, 10, v[84:85]
	v_mov_b32_e32 v48, v39
	v_mad_u64_u32 v[48:49], s[66:67], s31, 10, v[48:49]
	v_mov_b32_e32 v39, v48
	v_lshl_add_u64 v[52:53], v[38:39], 0, s[92:93]
	global_load_dwordx4 v[48:51], v[38:39], off offset:2048
	s_nop 0
	global_load_dwordx4 v[52:55], v[52:53], off offset:2048
.LBB0_541:
	s_or_b64 exec, exec, s[18:19]
	v_add_u32_e32 v37, 0xc0, v36
	s_movk_i32 s18, 0xff3f
	v_cmp_lt_i32_e32 vcc, s18, v36
	v_cmp_gt_i32_e64 s[18:19], s63, v37
	v_mov_b64_e32 v[62:63], v[2:3]
	v_mov_b64_e32 v[58:59], v[2:3]
	s_and_b64 s[66:67], vcc, s[18:19]
	v_mov_b64_e32 v[60:61], v[0:1]
	v_mov_b64_e32 v[56:57], v[0:1]
	s_and_saveexec_b64 s[18:19], s[66:67]
	s_nop 0
	v_mad_u64_u32 v[38:39], s[66:67], s30, 12, v[84:85]
	v_mov_b32_e32 v56, v39
	v_mad_u64_u32 v[56:57], s[66:67], s31, 12, v[56:57]
	v_mov_b32_e32 v39, v56
	v_lshl_add_u64 v[60:61], v[38:39], 0, s[92:93]
	global_load_dwordx4 v[56:59], v[38:39], off offset:2048
	s_nop 0
	global_load_dwordx4 v[60:63], v[60:61], off offset:2048
.LBB0_543:
	s_or_b64 exec, exec, s[18:19]
	v_add_u32_e32 v37, 0xe0, v36
	s_movk_i32 s18, 0xff1f
	v_cmp_lt_i32_e32 vcc, s18, v36
	v_cmp_gt_i32_e64 s[18:19], s63, v37
	v_mov_b64_e32 v[38:39], v[2:3]
	v_mov_b64_e32 v[66:67], v[2:3]
	s_and_b64 s[66:67], vcc, s[18:19]
	v_mov_b64_e32 v[36:37], v[0:1]
	v_mov_b64_e32 v[64:65], v[0:1]
	s_and_saveexec_b64 s[18:19], s[66:67]
	s_nop 0
	v_mad_u64_u32 v[36:37], s[66:67], s30, 14, v[84:85]
	v_mov_b32_e32 v38, v37
	v_mad_u64_u32 v[38:39], s[30:31], s31, 14, v[38:39]
	v_mov_b32_e32 v37, v38
	v_lshl_add_u64 v[38:39], v[36:37], 0, s[92:93]
	global_load_dwordx4 v[64:67], v[36:37], off offset:2048
	s_nop 0
	global_load_dwordx4 v[36:39], v[38:39], off offset:2048

.LBB0_546:
	ds_read_b128 v[232:235], v192
	ds_read_b128 v[236:239], v193
	s_nop 0
	s_nop 0
	s_lshl_b32 s26, s53, 7
	s_lshr_b32 s27, s33, s51
	s_cmp_eq_u32 s49, 0
	s_cselect_b64 s[18:19], -1, 0
	s_addk_i32 s50, 0xc0
	s_cmp_gt_i32 s50, s27
	s_cselect_b64 s[28:29], -1, 0
	s_nop 0
	ds_read_b128 v[246:249], v194
	s_waitcnt lgkmcnt(2)
	v_mfma_f32_16x16x32_bf16 v[132:135], v[232:235], v[128:131], 0
	s_or_b64 s[18:19], s[18:19], s[28:29]
	s_andn2_b64 vcc, exec, s[18:19]
	s_nop 0
	s_nop 0
	ds_read_b128 v[250:253], v195
	s_waitcnt lgkmcnt(2)
	v_mfma_f32_16x16x32_bf16 v[132:135], v[236:239], v[124:127], v[132:135]
	s_nop 0
	s_nop 0
	ds_read_b128 v[232:235], v192 offset:4096
	s_waitcnt lgkmcnt(2)
	v_mfma_f32_16x16x32_bf16 v[132:135], v[246:249], v[120:123], v[132:135]
	s_nop 0
	s_nop 0
	ds_read_b128 v[236:239], v193 offset:4096
	s_waitcnt lgkmcnt(2)
	v_mfma_f32_16x16x32_bf16 v[160:163], v[250:253], v[116:119], v[132:135]
	s_nop 4
	s_nop 0
	s_nop 0
	s_nop 0
	ds_read_b128 v[246:249], v194 offset:4096
	s_waitcnt lgkmcnt(2)
	v_mfma_f32_16x16x32_bf16 v[132:135], v[232:235], v[128:131], 0
	s_nop 0
	ds_read_b128 v[250:253], v195 offset:4096
	s_waitcnt lgkmcnt(2)
	v_mfma_f32_16x16x32_bf16 v[132:135], v[236:239], v[124:127], v[132:135]
	s_nop 0
	s_nop 0
	ds_read_b128 v[232:235], v192 offset:8192
	s_waitcnt lgkmcnt(2)
	v_mfma_f32_16x16x32_bf16 v[132:135], v[246:249], v[120:123], v[132:135]
	s_nop 0
	s_nop 0
	ds_read_b128 v[236:239], v193 offset:8192
	s_waitcnt lgkmcnt(2)
	v_mfma_f32_16x16x32_bf16 v[156:159], v[250:253], v[116:119], v[132:135]
	s_nop 4
	s_nop 0
	s_nop 0
	s_nop 0
	ds_read_b128 v[246:249], v194 offset:8192
	s_waitcnt lgkmcnt(2)
	v_mfma_f32_16x16x32_bf16 v[132:135], v[232:235], v[128:131], 0
	s_nop 0
	ds_read_b128 v[250:253], v195 offset:8192
	s_waitcnt lgkmcnt(2)
	v_mfma_f32_16x16x32_bf16 v[132:135], v[236:239], v[124:127], v[132:135]
	s_nop 0
	s_nop 0
	ds_read_b128 v[232:235], v192 offset:12288
	s_waitcnt lgkmcnt(2)
	v_mfma_f32_16x16x32_bf16 v[132:135], v[246:249], v[120:123], v[132:135]
	s_nop 0
	s_nop 0
	ds_read_b128 v[236:239], v193 offset:12288
	s_waitcnt lgkmcnt(2)
	v_mfma_f32_16x16x32_bf16 v[152:155], v[250:253], v[116:119], v[132:135]
	s_nop 4
	s_nop 0
	s_nop 0
	s_nop 0
	ds_read_b128 v[246:249], v194 offset:12288
	s_waitcnt lgkmcnt(2)
	v_mfma_f32_16x16x32_bf16 v[132:135], v[232:235], v[128:131], 0
	s_nop 0
	ds_read_b128 v[250:253], v195 offset:12288
	s_waitcnt lgkmcnt(2)
	v_mfma_f32_16x16x32_bf16 v[132:135], v[236:239], v[124:127], v[132:135]
	s_nop 0
	s_nop 0
	ds_read_b128 v[232:235], v192 offset:16384
	s_waitcnt lgkmcnt(2)
	v_mfma_f32_16x16x32_bf16 v[132:135], v[246:249], v[120:123], v[132:135]
	s_nop 0
	s_nop 0
	ds_read_b128 v[236:239], v193 offset:16384
	s_waitcnt lgkmcnt(2)
	v_mfma_f32_16x16x32_bf16 v[148:151], v[250:253], v[116:119], v[132:135]
	s_nop 4
	s_nop 0
	s_nop 0
	s_nop 0
	ds_read_b128 v[246:249], v194 offset:16384
	s_waitcnt lgkmcnt(2)
	v_mfma_f32_16x16x32_bf16 v[132:135], v[232:235], v[128:131], 0
	s_nop 0
	ds_read_b128 v[250:253], v195 offset:16384
	s_waitcnt lgkmcnt(2)
	v_mfma_f32_16x16x32_bf16 v[132:135], v[236:239], v[124:127], v[132:135]
	s_nop 0
	s_nop 0
	ds_read_b128 v[232:235], v192 offset:20480
	s_waitcnt lgkmcnt(2)
	v_mfma_f32_16x16x32_bf16 v[132:135], v[246:249], v[120:123], v[132:135]
	s_nop 0
	s_nop 0
	ds_read_b128 v[236:239], v193 offset:20480
	s_waitcnt lgkmcnt(2)
	v_mfma_f32_16x16x32_bf16 v[144:147], v[250:253], v[116:119], v[132:135]
	s_nop 4
	s_nop 0
	s_nop 0
	s_nop 0
	ds_read_b128 v[246:249], v194 offset:20480
	s_waitcnt lgkmcnt(2)
	v_mfma_f32_16x16x32_bf16 v[132:135], v[232:235], v[128:131], 0
	s_nop 0
	ds_read_b128 v[250:253], v195 offset:20480
	s_waitcnt lgkmcnt(2)
	v_mfma_f32_16x16x32_bf16 v[132:135], v[236:239], v[124:127], v[132:135]
	s_nop 0
	s_nop 0
	ds_read_b128 v[232:235], v192 offset:24576
	s_waitcnt lgkmcnt(2)
	v_mfma_f32_16x16x32_bf16 v[132:135], v[246:249], v[120:123], v[132:135]
	s_nop 0
	s_nop 0
	ds_read_b128 v[236:239], v193 offset:24576
	s_waitcnt lgkmcnt(2)
	v_mfma_f32_16x16x32_bf16 v[140:143], v[250:253], v[116:119], v[132:135]
	s_nop 4
	s_nop 0
	s_nop 0
	s_nop 0
	ds_read_b128 v[246:249], v194 offset:24576
	s_waitcnt lgkmcnt(2)
	v_mfma_f32_16x16x32_bf16 v[132:135], v[232:235], v[128:131], 0
	s_nop 0
	ds_read_b128 v[250:253], v195 offset:24576
	s_waitcnt lgkmcnt(2)
	v_mfma_f32_16x16x32_bf16 v[132:135], v[236:239], v[124:127], v[132:135]
	s_nop 0
	s_nop 0
	ds_read_b128 v[232:235], v192 offset:28672
	s_waitcnt lgkmcnt(2)
	v_mfma_f32_16x16x32_bf16 v[132:135], v[246:249], v[120:123], v[132:135]
	s_nop 0
	s_nop 0
	ds_read_b128 v[236:239], v193 offset:28672
	s_waitcnt lgkmcnt(2)
	v_mfma_f32_16x16x32_bf16 v[136:139], v[250:253], v[116:119], v[132:135]
	s_nop 4
	s_nop 0
	s_nop 0
	ds_read_b128 v[246:249], v194 offset:28672
	s_waitcnt lgkmcnt(2)
	v_mfma_f32_16x16x32_bf16 v[132:135], v[232:235], v[128:131], 0
	ds_read_b128 v[250:253], v195 offset:28672
	s_waitcnt lgkmcnt(2)
	v_mfma_f32_16x16x32_bf16 v[132:135], v[236:239], v[124:127], v[132:135]
	s_nop 0
	s_nop 0
	ds_read_b128 v[232:235], v192 offset:32768
	s_waitcnt lgkmcnt(2)
	v_mfma_f32_16x16x32_bf16 v[132:135], v[246:249], v[120:123], v[132:135]
	s_nop 0
	s_nop 0
	ds_read_b128 v[236:239], v193 offset:32768
	s_waitcnt lgkmcnt(2)
	v_mfma_f32_16x16x32_bf16 v[132:135], v[250:253], v[116:119], v[132:135]
	s_nop 0
	s_nop 0
	ds_read_b128 v[246:249], v194 offset:32768
	s_waitcnt lgkmcnt(2)
	v_mfma_f32_16x16x32_bf16 v[128:131], v[232:235], v[128:131], 0
	s_nop 0
	s_nop 0
	ds_read_b128 v[250:253], v195 offset:32768
	s_waitcnt lgkmcnt(2)
	v_mfma_f32_16x16x32_bf16 v[124:127], v[236:239], v[124:127], v[128:131]
	s_nop 4
	s_nop 0
	s_nop 0
	s_waitcnt lgkmcnt(1)
	v_mfma_f32_16x16x32_bf16 v[120:123], v[246:249], v[120:123], v[124:127]
	s_nop 2
	s_nop 0
	s_nop 0
	s_waitcnt lgkmcnt(0)
	v_mfma_f32_16x16x32_bf16 v[124:127], v[250:253], v[116:119], v[120:123]
	v_mov_b32_e32 v116, s89
	s_nop 1
	v_cndmask_b32_e64 v122, v160, v116, s[4:5]
	v_cndmask_b32_e64 v123, v161, v211, s[8:9]
	s_nop 2
	v_cndmask_b32_e64 v116, v124, v211, s[6:7]
	v_cndmask_b32_e64 v116, v116, v124, s[4:5]
	v_cndmask_b32_e64 v117, v211, v125, s[4:5]
	v_cndmask_b32_e64 v120, v162, v211, s[10:11]
	v_cndmask_b32_e64 v121, v163, v211, s[12:13]
	v_cndmask_b32_e64 v119, v125, v117, s[16:17]
	v_cndmask_b32_e64 v118, v124, v116, s[16:17]
	v_cndmask_b32_e64 v117, v127, v211, s[14:15]
	v_cndmask_b32_e64 v116, v126, v211, s[16:17]
	s_cbranch_vccnz .LBB0_519
	v_add_u32_e32 v125, v226, v184
	v_cmp_lt_i32_e32 vcc, 63, v226
	v_cmp_gt_i32_e64 s[18:19], s27, v125
	v_mov_b32_e32 v124, s89
	s_and_b64 s[18:19], vcc, s[18:19]
	v_cndmask_b32_e64 v122, v124, v122, s[18:19]
	v_or_b32_e32 v124, 1, v125
	v_cmp_gt_i32_e64 s[18:19], s27, v124
	s_and_b64 s[18:19], vcc, s[18:19]
	v_or_b32_e32 v124, 2, v125
	v_cndmask_b32_e64 v123, v211, v123, s[18:19]
	v_cmp_gt_i32_e64 s[18:19], s27, v124
	s_and_b64 s[18:19], vcc, s[18:19]
	v_or_b32_e32 v124, 3, v125
	v_cndmask_b32_e64 v120, v211, v120, s[18:19]
	v_cmp_gt_i32_e64 s[18:19], s27, v124
	s_and_b64 vcc, vcc, s[18:19]
	v_add_u32_e32 v125, v226, v185
	v_cndmask_b32_e32 v121, v211, v121, vcc
	v_cmp_lt_i32_e32 vcc, 47, v226
	v_cmp_gt_i32_e64 s[18:19], s27, v125
	v_mov_b32_e32 v124, s89
	s_and_b64 s[18:19], vcc, s[18:19]
	v_cndmask_b32_e64 v156, v124, v156, s[18:19]
	v_or_b32_e32 v124, 1, v125
	v_cmp_gt_i32_e64 s[18:19], s27, v124
	s_and_b64 s[18:19], vcc, s[18:19]
	v_or_b32_e32 v124, 2, v125
	v_cndmask_b32_e64 v157, v211, v157, s[18:19]
	v_cmp_gt_i32_e64 s[18:19], s27, v124
	s_and_b64 s[18:19], vcc, s[18:19]
	v_or_b32_e32 v124, 3, v125
	v_cndmask_b32_e64 v158, v211, v158, s[18:19]
	v_cmp_gt_i32_e64 s[18:19], s27, v124
	s_and_b64 vcc, vcc, s[18:19]
	v_add_u32_e32 v125, v226, v186
	v_cndmask_b32_e32 v159, v211, v159, vcc
	v_cmp_lt_i32_e32 vcc, 31, v226
	v_cmp_gt_i32_e64 s[18:19], s27, v125
	v_mov_b32_e32 v124, s89
	s_and_b64 s[18:19], vcc, s[18:19]
	v_cndmask_b32_e64 v152, v124, v152, s[18:19]
	v_or_b32_e32 v124, 1, v125
	v_cmp_gt_i32_e64 s[18:19], s27, v124
	s_and_b64 s[18:19], vcc, s[18:19]
	v_or_b32_e32 v124, 2, v125
	v_cndmask_b32_e64 v153, v211, v153, s[18:19]
	v_cmp_gt_i32_e64 s[18:19], s27, v124
	s_and_b64 s[18:19], vcc, s[18:19]
	v_or_b32_e32 v124, 3, v125
	v_cndmask_b32_e64 v154, v211, v154, s[18:19]
	v_cmp_gt_i32_e64 s[18:19], s27, v124
	s_and_b64 vcc, vcc, s[18:19]
	v_add_u32_e32 v125, v226, v187
	v_cndmask_b32_e32 v155, v211, v155, vcc
	v_cmp_lt_i32_e32 vcc, 15, v226
	v_cmp_gt_i32_e64 s[18:19], s27, v125
	v_mov_b32_e32 v124, s89
	s_and_b64 s[18:19], vcc, s[18:19]
	v_cndmask_b32_e64 v148, v124, v148, s[18:19]
	v_or_b32_e32 v124, 1, v125
	v_cmp_gt_i32_e64 s[18:19], s27, v124
	s_and_b64 s[18:19], vcc, s[18:19]
	v_or_b32_e32 v124, 2, v125
	v_cndmask_b32_e64 v149, v211, v149, s[18:19]
	v_cmp_gt_i32_e64 s[18:19], s27, v124
	s_and_b64 s[18:19], vcc, s[18:19]
	v_or_b32_e32 v124, 3, v125
	v_cndmask_b32_e64 v150, v211, v150, s[18:19]
	v_cmp_gt_i32_e64 s[18:19], s27, v124
	s_and_b64 vcc, vcc, s[18:19]
	v_or_b32_e32 v125, v226, v173
	v_cndmask_b32_e32 v151, v211, v151, vcc
	v_cmp_lt_i32_e32 vcc, -1, v226
	v_cmp_gt_i32_e64 s[18:19], s27, v125
	v_mov_b32_e32 v124, s89
	s_and_b64 s[18:19], vcc, s[18:19]
	v_cndmask_b32_e64 v144, v124, v144, s[18:19]
	v_or_b32_e32 v124, 1, v125
	v_cmp_gt_i32_e64 s[18:19], s27, v124
	s_and_b64 s[18:19], vcc, s[18:19]
	v_or_b32_e32 v124, 2, v125
	v_cndmask_b32_e64 v145, v211, v145, s[18:19]
	v_cmp_gt_i32_e64 s[18:19], s27, v124
	s_and_b64 s[18:19], vcc, s[18:19]
	v_or_b32_e32 v124, 3, v125
	v_cndmask_b32_e64 v146, v211, v146, s[18:19]
	v_cmp_gt_i32_e64 s[18:19], s27, v124
	s_and_b64 vcc, vcc, s[18:19]
	v_add_u32_e32 v125, v226, v188
	s_movk_i32 s18, 0xffef
	v_cndmask_b32_e32 v147, v211, v147, vcc
	v_cmp_lt_i32_e32 vcc, s18, v226
	v_cmp_gt_i32_e64 s[18:19], s27, v125
	v_mov_b32_e32 v124, s89
	s_and_b64 s[18:19], vcc, s[18:19]
	v_cndmask_b32_e64 v140, v124, v140, s[18:19]
	v_or_b32_e32 v124, 1, v125
	v_cmp_gt_i32_e64 s[18:19], s27, v124
	s_and_b64 s[18:19], vcc, s[18:19]
	v_or_b32_e32 v124, 2, v125
	v_cndmask_b32_e64 v141, v211, v141, s[18:19]
	v_cmp_gt_i32_e64 s[18:19], s27, v124
	s_and_b64 s[18:19], vcc, s[18:19]
	v_or_b32_e32 v124, 3, v125
	v_cndmask_b32_e64 v142, v211, v142, s[18:19]
	v_cmp_gt_i32_e64 s[18:19], s27, v124
	s_and_b64 vcc, vcc, s[18:19]
	v_add_u32_e32 v125, v226, v189
	s_movk_i32 s18, 0xffdf
	v_cndmask_b32_e32 v143, v211, v143, vcc
	v_cmp_lt_i32_e32 vcc, s18, v226
	v_cmp_gt_i32_e64 s[18:19], s27, v125
	v_mov_b32_e32 v124, s89
	s_and_b64 s[18:19], vcc, s[18:19]
	v_cndmask_b32_e64 v136, v124, v136, s[18:19]
	v_or_b32_e32 v124, 1, v125
	v_cmp_gt_i32_e64 s[18:19], s27, v124
	s_and_b64 s[18:19], vcc, s[18:19]
	v_or_b32_e32 v124, 2, v125
	v_cndmask_b32_e64 v137, v211, v137, s[18:19]
	v_cmp_gt_i32_e64 s[18:19], s27, v124
	s_and_b64 s[18:19], vcc, s[18:19]
	v_or_b32_e32 v124, 3, v125
	v_cndmask_b32_e64 v138, v211, v138, s[18:19]
	v_cmp_gt_i32_e64 s[18:19], s27, v124
	s_and_b64 vcc, vcc, s[18:19]
	v_add_u32_e32 v125, v226, v190
	s_movk_i32 s18, 0xffcf
	v_cndmask_b32_e32 v139, v211, v139, vcc
	v_cmp_lt_i32_e32 vcc, s18, v226
	v_cmp_gt_i32_e64 s[18:19], s27, v125
	v_mov_b32_e32 v124, s89
	s_and_b64 s[18:19], vcc, s[18:19]
	v_cndmask_b32_e64 v132, v124, v132, s[18:19]
	v_or_b32_e32 v124, 1, v125
	v_cmp_gt_i32_e64 s[18:19], s27, v124
	s_and_b64 s[18:19], vcc, s[18:19]
	v_or_b32_e32 v124, 2, v125
	v_cndmask_b32_e64 v133, v211, v133, s[18:19]
	v_cmp_gt_i32_e64 s[18:19], s27, v124
	s_and_b64 s[18:19], vcc, s[18:19]
	v_or_b32_e32 v124, 3, v125
	v_cndmask_b32_e64 v134, v211, v134, s[18:19]
	v_cmp_gt_i32_e64 s[18:19], s27, v124
	s_and_b64 vcc, vcc, s[18:19]
	v_add_u32_e32 v125, v226, v191
	s_movk_i32 s18, 0xffbf
	v_cndmask_b32_e32 v135, v211, v135, vcc
	v_cmp_lt_i32_e32 vcc, s18, v226
	v_cmp_gt_i32_e64 s[18:19], s27, v125
	v_mov_b32_e32 v124, s89
	s_and_b64 s[18:19], vcc, s[18:19]
	v_cndmask_b32_e64 v118, v124, v118, s[18:19]
	v_or_b32_e32 v124, 1, v125
	v_cmp_gt_i32_e64 s[18:19], s27, v124
	s_and_b64 s[18:19], vcc, s[18:19]
	v_or_b32_e32 v124, 2, v125
	v_cndmask_b32_e64 v119, v211, v119, s[18:19]
	v_cmp_gt_i32_e64 s[18:19], s27, v124
	s_and_b64 s[18:19], vcc, s[18:19]
	v_or_b32_e32 v124, 3, v125
	v_cndmask_b32_e64 v116, v211, v116, s[18:19]
	v_cmp_gt_i32_e64 s[18:19], s27, v124
	s_and_b64 vcc, vcc, s[18:19]
	v_cndmask_b32_e32 v117, v211, v117, vcc
	s_branch .LBB0_519
